# MFMA loop heads aligned to 64 bytes (instruction-fetch alignment of the hot K-loops)
# baseline (speedup 1.0000x reference)
.LBB0_195:
	s_ashr_i32 s35, s34, 31
	v_cmp_lt_i64_e32 vcc, s[36:37], v[140:141]
	s_lshl_b64 s[36:37], s[34:35], 19
	s_add_u32 s36, s47, s36
	s_addc_u32 s37, s60, s37
	s_and_b64 s[40:41], vcc, exec
	s_cselect_b32 s11, s37, s53
	s_cselect_b32 s13, s36, s52
	s_ashr_i32 s31, s30, 31
	s_lshl_b64 s[40:41], s[30:31], 19
	s_add_u32 s40, s20, s40
	s_addc_u32 s41, s21, s41
	s_and_b64 s[54:55], vcc, exec
	s_cselect_b32 s31, s41, s9
	s_cselect_b32 s35, s40, s8
	s_add_u32 s56, s8, 0x100
	s_addc_u32 s57, s9, 0
	s_add_u32 s8, s52, 0x40080
	v_mov_b32_e32 v0, 0
	s_addc_u32 s9, s53, 0
	s_mov_b32 s58, -2
	v_mov_b32_e32 v1, v0
	v_mov_b32_e32 v2, v0
	v_mov_b32_e32 v3, v0
	v_mov_b32_e32 v4, v0
	v_mov_b32_e32 v5, v0
	v_mov_b32_e32 v6, v0
	v_mov_b32_e32 v7, v0
	v_mov_b32_e32 v16, v0
	v_mov_b32_e32 v17, v0
	v_mov_b32_e32 v18, v0
	v_mov_b32_e32 v19, v0
	v_mov_b32_e32 v20, v0
	v_mov_b32_e32 v21, v0
	v_mov_b32_e32 v22, v0
	v_mov_b32_e32 v23, v0
	v_mov_b32_e32 v32, v0
	v_mov_b32_e32 v33, v0
	v_mov_b32_e32 v34, v0
	v_mov_b32_e32 v35, v0
	v_mov_b32_e32 v36, v0
	v_mov_b32_e32 v37, v0
	v_mov_b32_e32 v38, v0
	v_mov_b32_e32 v39, v0
	v_mov_b32_e32 v48, v0
	v_mov_b32_e32 v49, v0
	v_mov_b32_e32 v50, v0
	v_mov_b32_e32 v51, v0
	v_mov_b32_e32 v52, v0
	v_mov_b32_e32 v53, v0
	v_mov_b32_e32 v54, v0
	v_mov_b32_e32 v55, v0
	v_mov_b32_e32 v8, v0
	v_mov_b32_e32 v9, v0
	v_mov_b32_e32 v10, v0
	v_mov_b32_e32 v11, v0
	v_mov_b32_e32 v12, v0
	v_mov_b32_e32 v13, v0
	v_mov_b32_e32 v14, v0
	v_mov_b32_e32 v15, v0
	v_mov_b32_e32 v24, v0
	v_mov_b32_e32 v25, v0
	v_mov_b32_e32 v26, v0
	v_mov_b32_e32 v27, v0
	v_mov_b32_e32 v28, v0
	v_mov_b32_e32 v29, v0
	v_mov_b32_e32 v30, v0
	v_mov_b32_e32 v31, v0
	v_mov_b32_e32 v40, v0
	v_mov_b32_e32 v41, v0
	v_mov_b32_e32 v42, v0
	v_mov_b32_e32 v43, v0
	v_mov_b32_e32 v44, v0
	v_mov_b32_e32 v45, v0
	v_mov_b32_e32 v46, v0
	v_mov_b32_e32 v47, v0
	v_mov_b32_e32 v56, v0
	v_mov_b32_e32 v57, v0
	v_mov_b32_e32 v58, v0
	v_mov_b32_e32 v59, v0
	v_mov_b32_e32 v60, v0
	v_mov_b32_e32 v61, v0
	v_mov_b32_e32 v62, v0
	v_mov_b32_e32 v63, v0
	v_mov_b32_e32 v64, v0
	v_mov_b32_e32 v65, v0
	v_mov_b32_e32 v66, v0
	v_mov_b32_e32 v67, v0
	v_mov_b32_e32 v68, v0
	v_mov_b32_e32 v69, v0
	v_mov_b32_e32 v70, v0
	v_mov_b32_e32 v71, v0
	v_mov_b32_e32 v80, v0
	v_mov_b32_e32 v81, v0
	v_mov_b32_e32 v82, v0
	v_mov_b32_e32 v83, v0
	v_mov_b32_e32 v84, v0
	v_mov_b32_e32 v85, v0
	v_mov_b32_e32 v86, v0
	v_mov_b32_e32 v87, v0
	v_mov_b32_e32 v96, v0
	v_mov_b32_e32 v97, v0
	v_mov_b32_e32 v98, v0
	v_mov_b32_e32 v99, v0
	v_mov_b32_e32 v100, v0
	v_mov_b32_e32 v101, v0
	v_mov_b32_e32 v102, v0
	v_mov_b32_e32 v103, v0
	v_mov_b32_e32 v112, v0
	v_mov_b32_e32 v113, v0
	v_mov_b32_e32 v114, v0
	v_mov_b32_e32 v115, v0
	v_mov_b32_e32 v116, v0
	v_mov_b32_e32 v117, v0
	v_mov_b32_e32 v118, v0
	v_mov_b32_e32 v119, v0
	v_mov_b32_e32 v72, v0
	v_mov_b32_e32 v73, v0
	v_mov_b32_e32 v74, v0
	v_mov_b32_e32 v75, v0
	v_mov_b32_e32 v76, v0
	v_mov_b32_e32 v77, v0
	v_mov_b32_e32 v78, v0
	v_mov_b32_e32 v79, v0
	v_mov_b32_e32 v88, v0
	v_mov_b32_e32 v89, v0
	v_mov_b32_e32 v90, v0
	v_mov_b32_e32 v91, v0
	v_mov_b32_e32 v92, v0
	v_mov_b32_e32 v93, v0
	v_mov_b32_e32 v94, v0
	v_mov_b32_e32 v95, v0
	v_mov_b32_e32 v104, v0
	v_mov_b32_e32 v105, v0
	v_mov_b32_e32 v106, v0
	v_mov_b32_e32 v107, v0
	v_mov_b32_e32 v108, v0
	v_mov_b32_e32 v109, v0
	v_mov_b32_e32 v110, v0
	v_mov_b32_e32 v111, v0
	v_mov_b32_e32 v120, v0
	v_mov_b32_e32 v121, v0
	v_mov_b32_e32 v122, v0
	v_mov_b32_e32 v123, v0
	v_mov_b32_e32 v124, v0
	v_mov_b32_e32 v125, v0
	v_mov_b32_e32 v126, v0
	v_mov_b32_e32 v127, v0
	.p2align	6

.Lxbn2_end:
.LBB0_977:
	s_or_b64 exec, exec, s[4:5]
	s_mov_b64 s[20:21], s[0:1]
	v_mov_b32_e32 v133, v170
	s_waitcnt lgkmcnt(0)
	s_barrier
	s_load_dwordx2 s[4:5], s[20:21], 0x60
	v_and_b32_e32 v150, 63, v133
	v_lshlrev_b32_e32 v0, 2, v150
	s_waitcnt lgkmcnt(0)
	global_load_dword v1, v0, s[4:5]
	global_load_dword v2, v0, s[4:5] offset:256
	global_load_dword v3, v0, s[4:5] offset:512
	global_load_dword v4, v0, s[4:5] offset:768
	v_mbcnt_hi_u32_b32 v0, -1, v135
	v_and_b32_e32 v6, 64, v0
	v_xor_b32_e32 v5, 32, v0
	v_add_u32_e32 v6, 64, v6
	v_cmp_lt_i32_e32 vcc, v5, v6
	v_xor_b32_e32 v7, 16, v0
	v_xor_b32_e32 v8, 8, v0
	v_cndmask_b32_e32 v5, v0, v5, vcc
	v_lshlrev_b32_e32 v171, 2, v5
	v_cmp_lt_i32_e32 vcc, v7, v6
	v_xor_b32_e32 v9, 4, v0
	v_xor_b32_e32 v10, 2, v0
	v_cndmask_b32_e32 v7, v0, v7, vcc
	v_lshlrev_b32_e32 v172, 2, v7
	v_cmp_lt_i32_e32 vcc, v8, v6
	v_xor_b32_e32 v11, 1, v0
	s_mov_b32 s4, 0x3fb8aa3b
	s_mov_b32 s5, 0xc2ce8ed0
	s_mov_b32 s6, 0x42b17218
	s_waitcnt vmcnt(2)
	v_mul_f32_e32 v5, v1, v2
	ds_bpermute_b32 v5, v171, v5
	s_waitcnt vmcnt(0)
	v_mul_f32_e32 v12, v3, v4
	ds_bpermute_b32 v12, v171, v12
	s_waitcnt lgkmcnt(1)
	v_fmac_f32_e32 v5, v1, v2
	ds_bpermute_b32 v1, v172, v5
	s_waitcnt lgkmcnt(1)
	v_fmac_f32_e32 v12, v3, v4
	ds_bpermute_b32 v2, v172, v12
	v_cndmask_b32_e32 v3, v0, v8, vcc
	v_lshlrev_b32_e32 v173, 2, v3
	s_waitcnt lgkmcnt(1)
	v_add_f32_e32 v1, v5, v1
	ds_bpermute_b32 v3, v173, v1
	s_waitcnt lgkmcnt(1)
	v_add_f32_e32 v2, v12, v2
	ds_bpermute_b32 v4, v173, v2
	v_cmp_lt_i32_e32 vcc, v9, v6
	s_waitcnt lgkmcnt(1)
	v_add_f32_e32 v1, v1, v3
	v_cndmask_b32_e32 v5, v0, v9, vcc
	v_lshlrev_b32_e32 v174, 2, v5
	s_waitcnt lgkmcnt(0)
	v_add_f32_e32 v2, v2, v4
	ds_bpermute_b32 v3, v174, v1
	ds_bpermute_b32 v4, v174, v2
	v_cmp_lt_i32_e32 vcc, v10, v6
	s_waitcnt lgkmcnt(1)
	v_add_f32_e32 v1, v1, v3
	v_cndmask_b32_e32 v5, v0, v10, vcc
	v_lshlrev_b32_e32 v175, 2, v5
	s_waitcnt lgkmcnt(0)
	v_add_f32_e32 v2, v2, v4
	ds_bpermute_b32 v3, v175, v1
	ds_bpermute_b32 v4, v175, v2
	v_cmp_lt_i32_e32 vcc, v11, v6
	s_nop 1
	v_cndmask_b32_e32 v0, v0, v11, vcc
	v_lshlrev_b32_e32 v176, 2, v0
	s_waitcnt lgkmcnt(1)
	v_add_f32_e32 v0, v1, v3
	s_waitcnt lgkmcnt(0)
	v_add_f32_e32 v1, v2, v4
	ds_bpermute_b32 v2, v176, v0
	ds_bpermute_b32 v3, v176, v1
	v_mov_b32_e32 v4, 0x7f800000
	s_waitcnt lgkmcnt(1)
	v_add_f32_e32 v0, v0, v2
	s_waitcnt lgkmcnt(0)
	v_add_f32_e32 v1, v1, v3
	v_mul_f32_e32 v2, 0x3fb8aa3b, v0
	v_mul_f32_e32 v3, 0x3fb8aa3b, v1
	v_fma_f32 v5, v0, s4, -v2
	v_rndne_f32_e32 v6, v2
	v_fma_f32 v7, v1, s4, -v3
	v_rndne_f32_e32 v8, v3
	v_fmac_f32_e32 v5, 0x32a5705f, v0
	v_sub_f32_e32 v2, v2, v6
	v_fmac_f32_e32 v7, 0x32a5705f, v1
	v_sub_f32_e32 v3, v3, v8
	v_add_f32_e32 v2, v2, v5
	v_cvt_i32_f32_e32 v6, v6
	v_add_f32_e32 v3, v3, v7
	v_exp_f32_e32 v2, v2
	v_cvt_i32_f32_e32 v8, v8
	v_exp_f32_e32 v3, v3
	v_cmp_ngt_f32_e32 vcc, s5, v0
	v_ldexp_f32 v2, v2, v6
	s_and_b32 s4, s42, 7
	v_ldexp_f32 v3, v3, v8
	v_cndmask_b32_e32 v2, 0, v2, vcc
	v_cmp_ngt_f32_e32 vcc, s5, v1
	s_cmp_lg_u32 s4, 0
	s_mov_b32 s5, s2
	v_cndmask_b32_e32 v3, 0, v3, vcc
	v_cmp_nlt_f32_e32 vcc, s6, v0
	s_nop 1
	v_cndmask_b32_e32 v0, v4, v2, vcc
	v_cmp_nlt_f32_e32 vcc, s6, v1
	s_nop 1
	v_cndmask_b32_e32 v1, v4, v3, vcc
	v_sub_f32_e32 v0, v0, v1
	s_nop 0
	v_readfirstlane_b32 s4, v0
	v_mov_b32_e32 v0, 0x3e4ccccd
	v_add_f32_e32 v166, s4, v0
	s_branch .LBB0_1001
	.p2align	6

.LBB0_980:
	s_load_dwordx2 s[6:7], s[20:21], 0xe8
	s_lshl_b32 s45, s5, 2
	v_lshlrev_b32_e32 v130, 3, v133
	v_lshrrev_b32_e32 v0, 2, v133
	v_ashrrev_i32_e32 v131, 31, v130
	s_waitcnt lgkmcnt(0)
	s_add_u32 s47, s6, 0x919c000
	s_addc_u32 s52, s7, 0
	s_add_u32 s53, s6, 0x839c000
	s_addc_u32 s54, s7, 0
	s_add_u32 s22, s6, 0x779c000
	s_addc_u32 s23, s7, 0
	v_and_b32_e32 v0, 8, v0
	v_mov_b32_e32 v129, 0
	v_and_b32_e32 v2, 0x1f8, v130
	s_add_u32 s24, s6, 0xc99c000
	v_lshrrev_b32_e32 v1, 3, v133
	v_lshl_add_u64 v[4:5], v[130:131], 1, s[6:7]
	s_mov_b64 s[4:5], 0x91a8000
	v_and_b32_e32 v151, 31, v133
	v_lshlrev_b32_e32 v152, 4, v150
	s_addc_u32 s25, s7, 0
	v_and_b32_e32 v132, 4, v1
	s_lshl_b32 s55, s42, 2
	v_lshl_add_u64 v[134:135], v[4:5], 0, s[4:5]
	s_mov_b32 s5, 0
	v_lshlrev_b32_e32 v136, 1, v0
	v_mov_b32_e32 v137, v129
	v_lshlrev_b32_e32 v138, 1, v2
	v_mov_b32_e32 v139, v129
	s_mov_b64 s[26:27], 0x2000
	s_mov_b64 s[28:29], 0x4000
	s_mov_b64 s[30:31], 0x6000
	s_mov_b64 s[34:35], 0x8000
	s_mov_b64 s[36:37], 0xa000
	v_mov_b32_e32 v141, 0xbe38aa3b
	v_mov_b32_e32 v153, 0x358637bd
	s_mov_b32 s56, 0x800000
	s_branch .LBB0_982
	.p2align	6

.LBB0_982:
	v_readfirstlane_b32 s10, v133
	s_ashr_i32 s59, s10, 7
	s_add_i32 s4, s59, s45
	s_ashr_i32 s6, s4, 8
	s_bfe_u32 s8, s4, 0x20006
	s_lshl_b32 s7, s6, 11
	s_lshl_b32 s4, s4, 5
	s_addk_i32 s7, 0x1000
	s_lshl_b32 s6, s6, 9
	s_and_b32 s4, s4, 0x7e0
	s_add_i32 s6, s7, s6
	v_or_b32_e32 v0, s4, v151
	v_or_b32_e32 v142, s7, v0
	s_ashr_i32 s7, s6, 31
	s_bfe_u32 s58, s10, 0x10006
	v_ashrrev_i32_e32 v143, 31, v142
	s_lshl_b32 s57, s8, 7
	s_lshl_b32 s4, s8, 8
	s_lshl_b64 s[40:41], s[6:7], 10
	v_lshlrev_b64 v[0:1], 10, v[142:143]
	s_add_u32 s9, s53, s40
	v_lshl_add_u64 v[0:1], s[22:23], 0, v[0:1]
	s_addc_u32 s11, s54, s41
	v_lshl_add_u64 v[0:1], v[0:1], 0, s[4:5]
	s_add_u32 s6, s47, s40
	v_lshl_add_u64 v[0:1], v[0:1], 0, v[136:137]
	s_addc_u32 s7, s52, s41
	s_lshl_b32 s4, s58, 7
	v_lshl_add_u64 v[0:1], v[0:1], 0, s[4:5]
	global_load_dwordx4 v[112:115], v[0:1], off
	global_load_dwordx4 v[116:119], v[0:1], off offset:32
	global_load_dwordx4 v[120:123], v[0:1], off offset:64
	global_load_dwordx4 v[124:127], v[0:1], off offset:96
	s_mul_i32 s33, s8, 0xa0000
	s_add_u32 s6, s6, s33
	s_addc_u32 s7, s7, 0
	s_add_u32 s8, s9, s33
	s_addc_u32 s9, s11, 0
	s_ashr_i32 s4, s10, 6
	s_ashr_i32 s10, s10, 8
	s_and_b32 s11, s4, 3
	s_mulk_i32 s10, 0x140
	v_lshl_add_u64 v[0:1], v[130:131], 1, s[6:7]
	s_or_b32 s6, s10, s11
	s_ashr_i32 s7, s6, 31
	v_lshl_add_u64 v[144:145], s[8:9], 0, v[138:139]
	s_lshl_b64 s[8:9], s[6:7], 10
	s_lshl_b32 s4, s4, 10
	v_lshl_add_u64 v[2:3], v[144:145], 0, s[8:9]
	s_or_b32 s8, s6, 4
	s_add_i32 s4, s4, 0
	s_ashr_i32 s9, s8, 31
	s_barrier
	s_mov_b32 m0, s4
	s_lshl_b64 s[8:9], s[8:9], 10
	global_load_lds_dwordx4 v[2:3], off
	s_add_i32 m0, s4, 0x2000
	v_lshl_add_u64 v[2:3], v[144:145], 0, s[8:9]
	s_or_b32 s8, s6, 8
	global_load_lds_dwordx4 v[0:1], off
	s_add_i32 m0, s4, 0x4000
	s_ashr_i32 s9, s8, 31
	global_load_lds_dwordx4 v[2:3], off
	v_lshl_add_u64 v[2:3], v[0:1], 0, s[26:27]
	s_add_i32 m0, s4, 0x6000
	s_lshl_b64 s[8:9], s[8:9], 10
	global_load_lds_dwordx4 v[2:3], off
	v_lshl_add_u64 v[2:3], v[144:145], 0, s[8:9]
	s_or_b32 s8, s6, 12
	s_add_i32 m0, s4, 0x8000
	s_ashr_i32 s9, s8, 31
	global_load_lds_dwordx4 v[2:3], off
	v_lshl_add_u64 v[2:3], v[0:1], 0, s[28:29]
	s_add_i32 m0, s4, 0xa000
	s_lshl_b64 s[8:9], s[8:9], 10
	global_load_lds_dwordx4 v[2:3], off
	v_lshl_add_u64 v[2:3], v[144:145], 0, s[8:9]
	s_or_b32 s8, s6, 16
	s_add_i32 m0, s4, 0xc000
	s_ashr_i32 s9, s8, 31
	global_load_lds_dwordx4 v[2:3], off
	v_lshl_add_u64 v[2:3], v[0:1], 0, s[30:31]
	s_add_i32 m0, s4, 0xe000
	s_lshl_b64 s[8:9], s[8:9], 10
	s_or_b32 s6, s6, 20
	global_load_lds_dwordx4 v[2:3], off
	v_lshl_add_u64 v[2:3], v[144:145], 0, s[8:9]
	s_add_i32 m0, s4, 0x10000
	s_ashr_i32 s7, s6, 31
	global_load_lds_dwordx4 v[2:3], off
	v_lshl_add_u64 v[2:3], v[0:1], 0, s[34:35]
	s_add_i32 m0, s4, 0x12000
	s_lshl_b64 s[6:7], s[6:7], 10
	global_load_lds_dwordx4 v[2:3], off
	v_lshl_add_u64 v[2:3], v[144:145], 0, s[6:7]
	s_add_i32 m0, s4, 0x14000
	v_lshl_add_u64 v[0:1], v[0:1], 0, s[36:37]
	global_load_lds_dwordx4 v[2:3], off
	s_add_i32 m0, s4, 0x16000
	v_lshl_or_b32 v128, s58, 12, v152
	global_load_lds_dwordx4 v[0:1], off
	s_waitcnt vmcnt(8)
	s_barrier
	v_add_u32_e32 v154, 0, v128
	ds_read_b128 v[0:3], v154
	ds_read_b128 v[4:7], v154 offset:1024
	s_waitcnt vmcnt(0) lgkmcnt(0)
	v_mfma_f32_32x32x16_bf16 v[64:79], v[0:3], v[112:115], 0
	ds_read_b128 v[0:3], v154 offset:2048
	ds_read_b128 v[16:19], v154 offset:3072
	s_mov_b32 s4, s5
	s_mov_b32 s6, s5
	s_mov_b32 s7, s5
	s_mov_b32 s8, s5
	s_mov_b32 s9, s5
	v_mfma_f32_32x32x16_bf16 v[64:79], v[4:7], v[116:119], v[64:79]
	s_mov_b32 s10, s5
	s_mov_b32 s11, s5
	s_mov_b32 s12, s5
	s_mov_b32 s13, s5
	s_mov_b32 s14, s5
	s_mov_b32 s15, s5
	s_mov_b32 s16, s5
	s_waitcnt lgkmcnt(1)
	v_mfma_f32_32x32x16_bf16 v[64:79], v[0:3], v[120:123], v[64:79]
	s_mov_b32 s17, s5
	s_mov_b32 s18, s5
	s_mov_b32 s19, s5
	v_mov_b64_e32 v[0:1], s[4:5]
	v_mov_b64_e32 v[2:3], s[6:7]
	v_mov_b64_e32 v[4:5], s[8:9]
	v_mov_b64_e32 v[6:7], s[10:11]
	s_waitcnt lgkmcnt(0)
	v_mfma_f32_32x32x16_bf16 v[64:79], v[16:19], v[124:127], v[64:79]
	v_mov_b64_e32 v[8:9], s[12:13]
	v_mov_b64_e32 v[10:11], s[14:15]
	v_mov_b64_e32 v[12:13], s[16:17]
	v_mov_b64_e32 v[14:15], s[18:19]
	s_add_u32 s6, s33, s40
	s_addc_u32 s7, 0, s41
	v_mov_b64_e32 v[30:31], v[14:15]
	v_mov_b64_e32 v[46:47], v[14:15]
	v_mov_b64_e32 v[62:63], v[14:15]
	v_lshl_add_u64 v[146:147], v[134:135], 0, s[6:7]
	v_mov_b32_e32 v140, 0xf149f2ca
	s_mov_b32 s4, 28
	s_mov_b32 s10, 0x18000
	v_mov_b64_e32 v[28:29], v[12:13]
	v_mov_b64_e32 v[26:27], v[10:11]
	v_mov_b64_e32 v[24:25], v[8:9]
	v_mov_b64_e32 v[22:23], v[6:7]
	v_mov_b64_e32 v[20:21], v[4:5]
	v_mov_b64_e32 v[18:19], v[2:3]
	v_mov_b64_e32 v[16:17], v[0:1]
	v_mov_b64_e32 v[44:45], v[12:13]
	v_mov_b64_e32 v[42:43], v[10:11]
	v_mov_b64_e32 v[40:41], v[8:9]
	v_mov_b64_e32 v[38:39], v[6:7]
	v_mov_b64_e32 v[36:37], v[4:5]
	v_mov_b64_e32 v[34:35], v[2:3]
	v_mov_b64_e32 v[32:33], v[0:1]
	v_mov_b64_e32 v[60:61], v[12:13]
	v_mov_b64_e32 v[58:59], v[10:11]
	v_mov_b64_e32 v[56:57], v[8:9]
	v_mov_b64_e32 v[54:55], v[6:7]
	v_mov_b64_e32 v[52:53], v[4:5]
	v_mov_b64_e32 v[50:51], v[2:3]
	v_mov_b64_e32 v[48:49], v[0:1]
	v_mov_b32_e32 v148, 0
	s_mov_b32 s11, 0
	s_branch .LBB0_984
	.p2align	6

.LBB0_1003:
	s_or_b64 exec, exec, s[4:5]
	v_lshrrev_b32_e32 v1, 6, v0
	s_movk_i32 s6, 0x4400
	v_mul_lo_u32 v1, v1, s6
	v_lshrrev_b32_e32 v3, 1, v0
	v_and_b32_e32 v2, 63, v0
	v_and_b32_e32 v147, 15, v0
	v_add_u32_e32 v1, 0, v1
	v_and_b32_e32 v4, 24, v3
	v_lshrrev_b32_e32 v6, 2, v0
	v_lshlrev_b32_e32 v7, 3, v0
	v_mov_b32_e32 v145, 0
	v_add_u32_e32 v3, v1, v4
	v_lshlrev_b32_e32 v167, 1, v2
	v_mul_u32_u24_e32 v5, 0x110, v147
	v_and_b32_e32 v168, 31, v0
	v_and_b32_e32 v6, 8, v6
	v_and_b32_e32 v7, 0x1f8, v7
	v_lshrrev_b32_e32 v0, 3, v0
	v_cmp_eq_u32_e64 s[4:5], 0, v2
	v_cmp_gt_u32_e64 s[6:7], 32, v2
	v_and_b32_e32 v146, 4, v0
	v_add_u32_e32 v169, v1, v167
	v_lshlrev_b32_e32 v148, 4, v2
	v_mov_b32_e32 v149, v145
	s_add_i32 s40, 0, 0x22020
	v_lshlrev_b32_e32 v144, 2, v4
	s_mov_b64 s[10:11], 0x9f9c000
	s_mov_b64 s[12:13], 0x8000
	s_mov_b32 s41, 0x8000
	s_mov_b64 s[14:15], 0x10000
	s_mov_b64 s[16:17], 0x18000
	v_lshlrev_b32_e32 v150, 4, v2
	s_mov_b64 s[18:19], 0x76d8000
	s_movk_i32 s45, 0x1000
	s_mov_b64 s[22:23], 0xb79c000
	v_lshlrev_b32_e32 v152, 1, v6
	s_mov_b64 s[24:25], 0x779c000
	v_lshlrev_b32_e32 v177, 1, v7
	s_mov_b64 s[26:27], 0x839c000
	s_mov_b32 s47, 0x779c000
	s_mov_b32 s52, 0x919c000
	s_mov_b32 s53, 0x919d000
	v_mov_b32_e32 v178, 0x358637bd
	s_mov_b32 s54, 0x800000
	s_mov_b64 s[28:29], 0xc99c000
	s_mov_b32 s55, 0xc99c000
	v_add_u32_e32 v179, v3, v5
	s_waitcnt vmcnt(0) lgkmcnt(0)
	s_barrier
	s_branch .LBB0_1006
	.p2align	6

.LBB0_1027:
	global_load_dwordx4 v[16:19], v[62:63], off
	s_waitcnt vmcnt(7)
	v_mfma_f32_32x32x16_bf16 v[0:15], v[56:59], v[104:107], 0
	s_cmpk_lg_i32 s56, 0x4000
	s_cselect_b32 s8, s56, 0x3800
	v_lshl_add_u64 v[62:63], s[8:9], 1, v[156:157]
	v_add_co_u32_e32 v20, vcc, s41, v62
	v_mov_b32_e32 v71, v69
	s_nop 0
	v_addc_co_u32_e32 v21, vcc, 0, v63, vcc
	s_waitcnt vmcnt(6)
	v_mfma_f32_32x32x16_bf16 v[0:15], v[52:55], v[108:111], v[0:15]
	v_mov_b32_e32 v69, v68
	s_addk_i32 s56, 0x800
	s_cmpk_lg_i32 s56, 0x4800
	s_waitcnt vmcnt(2)
	v_mfma_f32_32x32x16_bf16 v[0:15], v[44:47], v[120:123], v[0:15]
	global_load_dwordx4 v[56:59], v[20:21], off
	global_load_dwordx4 v[52:55], v[20:21], off offset:1024
	global_load_dwordx4 v[44:47], v[20:21], off offset:2048
	s_waitcnt vmcnt(4)
	v_mfma_f32_32x32x16_bf16 v[0:15], v[36:39], v[124:127], v[0:15]
	global_load_dwordx4 v[36:39], v[20:21], off offset:3072
	s_nop 10
	v_max3_f32 v20, v0, v1, v2
	v_max3_f32 v20, v20, v3, v4
	v_max3_f32 v20, v20, v5, v6
	v_max3_f32 v20, v20, v7, v8
	v_max3_f32 v20, v20, v9, v10
	v_max3_f32 v68, v20, v11, v12
	v_max3_f32 v68, v68, v13, v14
	v_max3_f32 v68, v69, v68, v15
	v_mul_f32_e32 v73, 0xbe38aa3b, v68
	v_fmamk_f32 v1, v1, 0x3e38aa3b, v73
	v_fmamk_f32 v74, v4, 0x3e38aa3b, v73
	v_exp_f32_e32 v4, v1
	v_sub_f32_e32 v69, v69, v68
	v_mul_f32_e32 v69, 0x3e38aa3b, v69
	v_fmamk_f32 v70, v0, 0x3e38aa3b, v73
	v_exp_f32_e32 v0, v69
	v_fmamk_f32 v3, v3, 0x3e38aa3b, v73
	v_fmamk_f32 v5, v5, 0x3e38aa3b, v73
	v_fmamk_f32 v76, v8, 0x3e38aa3b, v73
	v_exp_f32_e32 v8, v3
	v_fmamk_f32 v72, v2, 0x3e38aa3b, v73
	v_fmamk_f32 v7, v7, 0x3e38aa3b, v73
	v_fmamk_f32 v79, v12, 0x3e38aa3b, v73
	v_exp_f32_e32 v2, v70
	v_exp_f32_e32 v12, v5
	v_fmamk_f32 v9, v9, 0x3e38aa3b, v73
	v_exp_f32_e32 v70, v7
	v_fmamk_f32 v75, v6, 0x3e38aa3b, v73
	v_fmamk_f32 v77, v10, 0x3e38aa3b, v73
	v_fmamk_f32 v11, v11, 0x3e38aa3b, v73
	v_exp_f32_e32 v6, v72
	v_exp_f32_e32 v10, v74
	v_exp_f32_e32 v74, v9
	v_fmamk_f32 v13, v13, 0x3e38aa3b, v73
	v_exp_f32_e32 v78, v11
	v_exp_f32_e32 v90, v13
	v_fmamk_f32 v89, v14, 0x3e38aa3b, v73
	v_fmac_f32_e32 v73, 0x3e38aa3b, v15
	v_exp_f32_e32 v14, v75
	v_exp_f32_e32 v72, v76
	v_exp_f32_e32 v94, v73
	v_exp_f32_e32 v76, v77
	v_exp_f32_e32 v88, v79
	v_exp_f32_e32 v92, v89
	s_waitcnt vmcnt(4)
	v_mfma_f32_32x32x16_bf16 v[16:31], v[16:19], v[116:119], 0
	v_mfma_f32_32x32x16_bf16 v[16:31], v[48:51], v[112:115], v[16:31]
	v_mfma_f32_32x32x16_bf16 v[16:31], v[40:43], v[96:99], v[16:31]
	global_load_dwordx4 v[48:51], v[62:63], off offset:1024
	global_load_dwordx4 v[40:43], v[62:63], off offset:2048
	v_mfma_f32_32x32x16_bf16 v[16:31], v[32:35], v[100:103], v[16:31]
	global_load_dwordx4 v[32:35], v[62:63], off offset:3072
	s_nop 10
	v_max3_f32 v1, v16, v17, v18
	v_max3_f32 v1, v1, v19, v20
	v_max3_f32 v1, v1, v21, v22
	v_max3_f32 v1, v1, v23, v24
	v_max3_f32 v1, v1, v25, v26
	v_max3_f32 v1, v1, v27, v28
	v_max3_f32 v1, v1, v29, v30
	v_max3_f32 v69, v71, v1, v31
	v_sub_f32_e32 v1, v71, v69
	v_mul_f32_e32 v95, 0xbe38aa3b, v69
	v_mul_f32_e32 v1, 0x3e38aa3b, v1
	v_fmamk_f32 v3, v16, 0x3e38aa3b, v95
	v_fmamk_f32 v5, v17, 0x3e38aa3b, v95
	v_exp_f32_e32 v1, v1
	v_exp_f32_e32 v3, v3
	v_fmamk_f32 v7, v18, 0x3e38aa3b, v95
	v_exp_f32_e32 v5, v5
	v_fmamk_f32 v9, v19, 0x3e38aa3b, v95
	v_exp_f32_e32 v7, v7
	v_fmamk_f32 v11, v20, 0x3e38aa3b, v95
	v_exp_f32_e32 v9, v9
	v_fmamk_f32 v13, v21, 0x3e38aa3b, v95
	v_exp_f32_e32 v11, v11
	v_pk_fma_f32 v[0:1], v[60:61], v[0:1], v[2:3]
	v_fmamk_f32 v15, v22, 0x3e38aa3b, v95
	v_exp_f32_e32 v13, v13
	v_pk_add_f32 v[0:1], v[4:5], v[0:1]
	v_fmamk_f32 v16, v23, 0x3e38aa3b, v95
	v_exp_f32_e32 v15, v15
	v_pk_add_f32 v[0:1], v[6:7], v[0:1]
	v_fmamk_f32 v17, v24, 0x3e38aa3b, v95
	v_exp_f32_e32 v71, v16
	v_pk_add_f32 v[0:1], v[8:9], v[0:1]
	v_fmamk_f32 v18, v25, 0x3e38aa3b, v95
	v_exp_f32_e32 v73, v17
	v_pk_add_f32 v[0:1], v[10:11], v[0:1]
	v_fmamk_f32 v19, v26, 0x3e38aa3b, v95
	v_exp_f32_e32 v75, v18
	v_pk_add_f32 v[0:1], v[12:13], v[0:1]
	v_fmamk_f32 v20, v27, 0x3e38aa3b, v95
	v_exp_f32_e32 v77, v19
	v_pk_add_f32 v[0:1], v[14:15], v[0:1]
	v_fmamk_f32 v21, v28, 0x3e38aa3b, v95
	v_exp_f32_e32 v79, v20
	v_pk_add_f32 v[0:1], v[70:71], v[0:1]
	v_fmamk_f32 v22, v29, 0x3e38aa3b, v95
	v_exp_f32_e32 v89, v21
	v_pk_add_f32 v[0:1], v[72:73], v[0:1]
	v_fmamk_f32 v23, v30, 0x3e38aa3b, v95
	v_exp_f32_e32 v91, v22
	v_pk_add_f32 v[0:1], v[74:75], v[0:1]
	v_fmac_f32_e32 v95, 0x3e38aa3b, v31
	v_exp_f32_e32 v93, v23
	v_pk_add_f32 v[0:1], v[76:77], v[0:1]
	v_exp_f32_e32 v95, v95
	v_pk_add_f32 v[0:1], v[78:79], v[0:1]
	s_nop 0
	v_pk_add_f32 v[0:1], v[88:89], v[0:1]
	s_nop 0
	v_pk_add_f32 v[0:1], v[90:91], v[0:1]
	s_nop 0
	v_pk_add_f32 v[0:1], v[92:93], v[0:1]
	s_nop 0
	v_pk_add_f32 v[60:61], v[94:95], v[0:1]
	s_cbranch_scc1 .LBB0_1027
	ds_bpermute_b32 v0, v171, v69
	v_max_f32_e32 v2, v69, v69
	ds_bpermute_b32 v1, v171, v61
	ds_bpermute_b32 v4, v171, v68
	v_max_f32_e32 v9, v68, v68
	s_waitcnt lgkmcnt(2)
	v_max_f32_e32 v3, v0, v0
	v_max_f32_e32 v2, v2, v3
	v_sub_f32_e32 v0, v0, v2
	v_sub_f32_e32 v3, v69, v2
	v_mul_f32_e32 v0, 0x3e38aa3b, v0
	v_mul_f32_e32 v3, 0x3e38aa3b, v3
	v_exp_f32_e32 v0, v0
	v_exp_f32_e32 v3, v3
	s_waitcnt lgkmcnt(0)
	v_max_f32_e32 v8, v4, v4
	v_max_f32_e32 v8, v9, v8
	v_mul_f32_e32 v0, v0, v1
	v_fmac_f32_e32 v0, v61, v3
	v_div_scale_f32 v1, s[56:57], v0, v0, 1.0
	v_rcp_f32_e32 v3, v1
	v_sub_f32_e32 v4, v4, v8
	ds_bpermute_b32 v7, v171, v60
	v_sub_f32_e32 v9, v68, v8
	v_fma_f32 v5, -v1, v3, 1.0
	v_mul_f32_e32 v4, 0x3e38aa3b, v4
	v_mul_f32_e32 v151, 0xbe38aa3b, v2
	v_div_scale_f32 v2, vcc, 1.0, v0, 1.0
	v_fmac_f32_e32 v3, v5, v3
	v_mul_f32_e32 v9, 0x3e38aa3b, v9
	v_exp_f32_e32 v4, v4
	v_mul_f32_e32 v5, v2, v3
	v_exp_f32_e32 v9, v9
	v_fma_f32 v6, -v1, v5, v2
	v_fmac_f32_e32 v5, v6, v3
	v_fma_f32 v1, -v1, v5, v2
	s_waitcnt lgkmcnt(0)
	v_mul_f32_e32 v2, v4, v7
	v_fmac_f32_e32 v2, v60, v9
	v_div_scale_f32 v4, s[56:57], v2, v2, v166
	v_rcp_f32_e32 v6, v4
	v_div_fmas_f32 v1, v1, v3, v5
	v_div_fixup_f32 v158, v1, v0, 1.0
	s_lshl_b32 s8, s36, 13
	v_fma_f32 v0, -v4, v6, 1.0
	v_fmac_f32_e32 v6, v0, v6
	v_div_scale_f32 v0, vcc, v166, v2, v166
	v_mul_f32_e32 v1, v0, v6
	v_fma_f32 v3, -v4, v1, v0
	v_fmac_f32_e32 v1, v3, v6
	v_fma_f32 v0, -v4, v1, v0
	s_and_b32 s8, s8, 0x30000
	v_div_fmas_f32 v0, v0, v6, v1
	s_add_u32 s34, s8, s34
	v_div_fixup_f32 v160, v0, v2, v166
	v_lshl_add_u64 v[0:1], s[30:31], 0, v[148:149]
	s_addc_u32 s35, 0, s35
	v_lshl_add_u64 v[162:163], v[0:1], 0, s[34:35]
	v_mov_b32_e32 v0, 0
	v_mul_f32_e32 v153, 0xbe38aa3b, v8
	v_mov_b32_e32 v159, v158
	v_mov_b32_e32 v161, v160
	s_mov_b64 s[34:35], 0
	s_movk_i32 s36, 0x800
	v_mov_b64_e32 v[164:165], v[156:157]
	v_mov_b32_e32 v1, v0
	v_mov_b32_e32 v2, v0
	v_mov_b32_e32 v3, v0
	v_mov_b32_e32 v4, v0
	v_mov_b32_e32 v5, v0
	v_mov_b32_e32 v6, v0
	v_mov_b32_e32 v7, v0
	v_mov_b32_e32 v8, v0
	v_mov_b32_e32 v9, v0
	v_mov_b32_e32 v10, v0
	v_mov_b32_e32 v11, v0
	v_mov_b32_e32 v12, v0
	v_mov_b32_e32 v13, v0
	v_mov_b32_e32 v14, v0
	v_mov_b32_e32 v15, v0
	v_mov_b32_e32 v16, v0
	v_mov_b32_e32 v17, v0
	v_mov_b32_e32 v18, v0
	v_mov_b32_e32 v19, v0
	v_mov_b32_e32 v20, v0
	v_mov_b32_e32 v21, v0
	v_mov_b32_e32 v22, v0
	v_mov_b32_e32 v23, v0
	v_mov_b32_e32 v24, v0
	v_mov_b32_e32 v25, v0
	v_mov_b32_e32 v26, v0
	v_mov_b32_e32 v27, v0
	v_mov_b32_e32 v28, v0
	v_mov_b32_e32 v29, v0
	v_mov_b32_e32 v30, v0
	v_mov_b32_e32 v31, v0
	s_waitcnt vmcnt(0)
	v_mov_b32_e32 v32, v0
	v_mov_b32_e32 v33, v0
	v_mov_b32_e32 v34, v0
	v_mov_b32_e32 v35, v0
	v_mov_b32_e32 v36, v0
	v_mov_b32_e32 v37, v0
	v_mov_b32_e32 v38, v0
	v_mov_b32_e32 v39, v0
	v_mov_b32_e32 v40, v0
	v_mov_b32_e32 v41, v0
	v_mov_b32_e32 v42, v0
	v_mov_b32_e32 v43, v0
	v_mov_b32_e32 v44, v0
	v_mov_b32_e32 v45, v0
	v_mov_b32_e32 v46, v0
	v_mov_b32_e32 v47, v0
	v_mov_b32_e32 v48, v0
	v_mov_b32_e32 v49, v0
	v_mov_b32_e32 v50, v0
	v_mov_b32_e32 v51, v0
	v_mov_b32_e32 v52, v0
	v_mov_b32_e32 v53, v0
	v_mov_b32_e32 v54, v0
	v_mov_b32_e32 v55, v0
	v_mov_b32_e32 v56, v0
	v_mov_b32_e32 v57, v0
	v_mov_b32_e32 v58, v0
	v_mov_b32_e32 v59, v0
	v_mov_b32_e32 v60, v0
	v_mov_b32_e32 v61, v0
	v_mov_b32_e32 v62, v0
	v_mov_b32_e32 v63, v0
	.p2align	6

.LBB0_1176:
	s_ashr_i32 s23, s22, 31
	v_cmp_lt_i64_e32 vcc, s[24:25], v[136:137]
	s_lshl_b64 s[24:25], s[22:23], 18
	s_add_u32 s24, s14, s24
	s_addc_u32 s25, s15, s25
	s_and_b64 s[26:27], vcc, exec
	s_cselect_b32 s23, s25, s11
	s_cselect_b32 s57, s24, s10
	s_ashr_i32 s21, s20, 31
	s_lshl_b64 s[26:27], s[20:21], 18
	s_add_u32 s26, s31, s26
	s_addc_u32 s27, s34, s27
	s_and_b64 s[28:29], vcc, exec
	s_cselect_b32 s21, s27, s9
	s_cselect_b32 s58, s26, s8
	s_add_u32 s59, s8, 0x100
	s_addc_u32 s60, s9, 0
	s_add_u32 s8, s10, 0x20080
	v_mov_b32_e32 v0, 0
	s_addc_u32 s9, s11, 0
	s_mov_b32 s61, -2
	v_mov_b32_e32 v1, v0
	v_mov_b32_e32 v2, v0
	v_mov_b32_e32 v3, v0
	v_mov_b32_e32 v4, v0
	v_mov_b32_e32 v5, v0
	v_mov_b32_e32 v6, v0
	v_mov_b32_e32 v7, v0
	v_mov_b32_e32 v8, v0
	v_mov_b32_e32 v9, v0
	v_mov_b32_e32 v10, v0
	v_mov_b32_e32 v11, v0
	v_mov_b32_e32 v12, v0
	v_mov_b32_e32 v13, v0
	v_mov_b32_e32 v14, v0
	v_mov_b32_e32 v15, v0
	v_mov_b32_e32 v16, v0
	v_mov_b32_e32 v17, v0
	v_mov_b32_e32 v18, v0
	v_mov_b32_e32 v19, v0
	v_mov_b32_e32 v20, v0
	v_mov_b32_e32 v21, v0
	v_mov_b32_e32 v22, v0
	v_mov_b32_e32 v23, v0
	v_mov_b32_e32 v24, v0
	v_mov_b32_e32 v25, v0
	v_mov_b32_e32 v26, v0
	v_mov_b32_e32 v27, v0
	v_mov_b32_e32 v28, v0
	v_mov_b32_e32 v29, v0
	v_mov_b32_e32 v30, v0
	v_mov_b32_e32 v31, v0
	v_mov_b32_e32 v32, v0
	v_mov_b32_e32 v33, v0
	v_mov_b32_e32 v34, v0
	v_mov_b32_e32 v35, v0
	v_mov_b32_e32 v36, v0
	v_mov_b32_e32 v37, v0
	v_mov_b32_e32 v38, v0
	v_mov_b32_e32 v39, v0
	v_mov_b32_e32 v40, v0
	v_mov_b32_e32 v41, v0
	v_mov_b32_e32 v42, v0
	v_mov_b32_e32 v43, v0
	v_mov_b32_e32 v44, v0
	v_mov_b32_e32 v45, v0
	v_mov_b32_e32 v46, v0
	v_mov_b32_e32 v47, v0
	v_mov_b32_e32 v48, v0
	v_mov_b32_e32 v49, v0
	v_mov_b32_e32 v50, v0
	v_mov_b32_e32 v51, v0
	v_mov_b32_e32 v52, v0
	v_mov_b32_e32 v53, v0
	v_mov_b32_e32 v54, v0
	v_mov_b32_e32 v55, v0
	v_mov_b32_e32 v56, v0
	v_mov_b32_e32 v57, v0
	v_mov_b32_e32 v58, v0
	v_mov_b32_e32 v59, v0
	v_mov_b32_e32 v60, v0
	v_mov_b32_e32 v61, v0
	v_mov_b32_e32 v62, v0
	v_mov_b32_e32 v63, v0
	v_mov_b32_e32 v64, v0
	v_mov_b32_e32 v65, v0
	v_mov_b32_e32 v66, v0
	v_mov_b32_e32 v67, v0
	v_mov_b32_e32 v68, v0
	v_mov_b32_e32 v69, v0
	v_mov_b32_e32 v70, v0
	v_mov_b32_e32 v71, v0
	v_mov_b32_e32 v72, v0
	v_mov_b32_e32 v73, v0
	v_mov_b32_e32 v74, v0
	v_mov_b32_e32 v75, v0
	v_mov_b32_e32 v76, v0
	v_mov_b32_e32 v77, v0
	v_mov_b32_e32 v78, v0
	v_mov_b32_e32 v79, v0
	v_mov_b32_e32 v80, v0
	v_mov_b32_e32 v81, v0
	v_mov_b32_e32 v82, v0
	v_mov_b32_e32 v83, v0
	v_mov_b32_e32 v84, v0
	v_mov_b32_e32 v85, v0
	v_mov_b32_e32 v86, v0
	v_mov_b32_e32 v87, v0
	v_mov_b32_e32 v88, v0
	v_mov_b32_e32 v89, v0
	v_mov_b32_e32 v90, v0
	v_mov_b32_e32 v91, v0
	v_mov_b32_e32 v92, v0
	v_mov_b32_e32 v93, v0
	v_mov_b32_e32 v94, v0
	v_mov_b32_e32 v95, v0
	v_mov_b32_e32 v96, v0
	v_mov_b32_e32 v97, v0
	v_mov_b32_e32 v98, v0
	v_mov_b32_e32 v99, v0
	v_mov_b32_e32 v100, v0
	v_mov_b32_e32 v101, v0
	v_mov_b32_e32 v102, v0
	v_mov_b32_e32 v103, v0
	v_mov_b32_e32 v104, v0
	v_mov_b32_e32 v105, v0
	v_mov_b32_e32 v106, v0
	v_mov_b32_e32 v107, v0
	v_mov_b32_e32 v108, v0
	v_mov_b32_e32 v109, v0
	v_mov_b32_e32 v110, v0
	v_mov_b32_e32 v111, v0
	v_mov_b32_e32 v112, v0
	v_mov_b32_e32 v113, v0
	v_mov_b32_e32 v114, v0
	v_mov_b32_e32 v115, v0
	v_mov_b32_e32 v116, v0
	v_mov_b32_e32 v117, v0
	v_mov_b32_e32 v118, v0
	v_mov_b32_e32 v119, v0
	v_mov_b32_e32 v120, v0
	v_mov_b32_e32 v121, v0
	v_mov_b32_e32 v122, v0
	v_mov_b32_e32 v123, v0
	v_mov_b32_e32 v124, v0
	v_mov_b32_e32 v125, v0
	v_mov_b32_e32 v126, v0
	v_mov_b32_e32 v127, v0
	.p2align	6

.LBB0_1237:
	s_and_b32 s20, s16, 3
	s_mov_b64 s[16:17], 0x80
	s_add_i32 m0, s58, 0x18000
	v_lshl_add_u64 v[6:7], v[6:7], 0, s[16:17]
	s_lshl_b32 s21, s5, 13
	s_lshl_b32 s22, s20, 12
	s_waitcnt vmcnt(4)
	s_barrier
	global_load_lds_dwordx4 v[6:7], off
	v_lshl_add_u64 v[4:5], v[4:5], 0, s[16:17]
	s_add_i32 m0, s58, 0x1a000
	s_add_i32 s62, s58, 0x8000
	s_add_i32 s63, s58, 0xa000
	global_load_lds_dwordx4 v[4:5], off
	v_lshl_add_u64 v[2:3], v[2:3], 0, s[16:17]
	s_mov_b32 m0, s62
	s_add_u32 s18, s36, 0x40080
	global_load_lds_dwordx4 v[2:3], off
	v_lshl_add_u64 v[0:1], v[0:1], 0, s[16:17]
	s_mov_b32 m0, s63
	s_addc_u32 s19, s37, 0
	global_load_lds_dwordx4 v[0:1], off
	s_add_i32 m0, s58, 0x1c000
	v_lshl_add_u64 v[0:1], s[18:19], 0, v[130:131]
	global_load_lds_dwordx4 v[0:1], off
	v_lshl_add_u64 v[0:1], s[18:19], 0, v[128:129]
	s_add_i32 m0, s58, 0x1e000
	s_ashr_i32 s64, s42, 31
	global_load_lds_dwordx4 v[0:1], off
	v_bfe_u32 v1, v8, 4, 2
	v_and_b32_e32 v0, 15, v8
	v_lshlrev_b32_e32 v2, 4, v1
	v_lshl_or_b32 v152, s5, 6, v0
	v_lshl_or_b32 v0, v0, 6, v2
	v_lshlrev_b32_e32 v2, 2, v8
	v_and_b32_e32 v2, 32, v2
	v_bitop3_b32 v3, v0, s21, v2 bitop3:0xde
	v_bitop3_b32 v153, v0, s22, v2 bitop3:0xde
	v_lshlrev_b32_e32 v0, 2, v1
	v_lshl_or_b32 v154, s20, 5, v0
	v_lshlrev_b32_e32 v0, 14, v9
	v_and_b32_e32 v0, 0xffff8000, v0
	v_lshl_add_u32 v0, v10, 11, v0
	v_and_b32_e32 v1, 1, v9
	v_lshl_or_b32 v0, v1, 6, v0
	v_lshl_add_u32 v134, v11, 1, v0
	v_lshlrev_b32_e32 v0, 14, v12
	v_and_b32_e32 v0, 0xffff8000, v0
	s_waitcnt vmcnt(6)
	s_add_u32 s66, s8, 0x780000
	v_lshl_add_u32 v0, v13, 11, v0
	v_and_b32_e32 v1, 1, v12
	s_addc_u32 s67, s9, 0
	v_lshl_or_b32 v0, v1, 6, v0
	s_add_i32 s68, 0, 0x10000
	s_add_i32 s69, 0, 0x14000
	s_sext_i32_i8 s76, s4
	s_mov_b32 s65, s42
	v_mov_b32_e32 v135, v133
	v_lshl_add_u32 v136, v14, 1, v0
	v_mov_b32_e32 v137, v133
	v_mov_b64_e32 v[138:139], 0xc0
	v_mov_b64_e32 v[140:141], 0xbf
	v_add_u32_e32 v155, s68, v153
	v_add_u32_e32 v156, 0, v3
	v_add_u32_e32 v157, s69, v153
	s_movk_i32 s70, 0x1000
	s_mov_b64 s[18:19], 0x80000
	s_movk_i32 s71, 0xf80
	s_mov_b64 s[20:21], 0x90000
	s_movk_i32 s72, 0xf70
	s_mov_b64 s[22:23], 0xa0000
	s_movk_i32 s73, 0xf60
	s_mov_b64 s[24:25], 0xb0000
	s_movk_i32 s74, 0xf50
	s_mov_b32 s75, 0
	s_barrier
	.p2align	6

.LBB0_1240:
	s_ashr_i32 s29, s28, 31
	v_cmp_lt_i64_e32 vcc, s[30:31], v[138:139]
	s_lshl_b64 s[30:31], s[28:29], 19
	s_add_u32 s30, s55, s30
	s_addc_u32 s31, s56, s31
	s_and_b64 s[34:35], vcc, exec
	s_cselect_b32 s29, s31, s41
	s_cselect_b32 s77, s30, s40
	s_ashr_i32 s27, s26, 31
	s_lshl_b64 s[34:35], s[26:27], 19
	s_add_u32 s34, s47, s34
	s_addc_u32 s35, s54, s35
	s_and_b64 s[52:53], vcc, exec
	s_cselect_b32 s27, s35, s37
	s_cselect_b32 s78, s34, s36
	s_add_u32 s79, s36, 0x100
	s_addc_u32 s80, s37, 0
	s_add_u32 s36, s40, 0x40080
	v_mov_b32_e32 v0, 0
	s_addc_u32 s37, s41, 0
	s_mov_b32 s81, -2
	v_mov_b32_e32 v1, v0
	v_mov_b32_e32 v2, v0
	v_mov_b32_e32 v3, v0
	v_mov_b32_e32 v4, v0
	v_mov_b32_e32 v5, v0
	v_mov_b32_e32 v6, v0
	v_mov_b32_e32 v7, v0
	v_mov_b32_e32 v8, v0
	v_mov_b32_e32 v9, v0
	v_mov_b32_e32 v10, v0
	v_mov_b32_e32 v11, v0
	v_mov_b32_e32 v12, v0
	v_mov_b32_e32 v13, v0
	v_mov_b32_e32 v14, v0
	v_mov_b32_e32 v15, v0
	v_mov_b32_e32 v16, v0
	v_mov_b32_e32 v17, v0
	v_mov_b32_e32 v18, v0
	v_mov_b32_e32 v19, v0
	v_mov_b32_e32 v20, v0
	v_mov_b32_e32 v21, v0
	v_mov_b32_e32 v22, v0
	v_mov_b32_e32 v23, v0
	v_mov_b32_e32 v24, v0
	v_mov_b32_e32 v25, v0
	v_mov_b32_e32 v26, v0
	v_mov_b32_e32 v27, v0
	v_mov_b32_e32 v28, v0
	v_mov_b32_e32 v29, v0
	v_mov_b32_e32 v30, v0
	v_mov_b32_e32 v31, v0
	v_mov_b32_e32 v32, v0
	v_mov_b32_e32 v33, v0
	v_mov_b32_e32 v34, v0
	v_mov_b32_e32 v35, v0
	v_mov_b32_e32 v36, v0
	v_mov_b32_e32 v37, v0
	v_mov_b32_e32 v38, v0
	v_mov_b32_e32 v39, v0
	v_mov_b32_e32 v40, v0
	v_mov_b32_e32 v41, v0
	v_mov_b32_e32 v42, v0
	v_mov_b32_e32 v43, v0
	v_mov_b32_e32 v44, v0
	v_mov_b32_e32 v45, v0
	v_mov_b32_e32 v46, v0
	v_mov_b32_e32 v47, v0
	v_mov_b32_e32 v48, v0
	v_mov_b32_e32 v49, v0
	v_mov_b32_e32 v50, v0
	v_mov_b32_e32 v51, v0
	v_mov_b32_e32 v52, v0
	v_mov_b32_e32 v53, v0
	v_mov_b32_e32 v54, v0
	v_mov_b32_e32 v55, v0
	v_mov_b32_e32 v56, v0
	v_mov_b32_e32 v57, v0
	v_mov_b32_e32 v58, v0
	v_mov_b32_e32 v59, v0
	v_mov_b32_e32 v60, v0
	v_mov_b32_e32 v61, v0
	v_mov_b32_e32 v62, v0
	v_mov_b32_e32 v63, v0
	v_mov_b32_e32 v64, v0
	v_mov_b32_e32 v65, v0
	v_mov_b32_e32 v66, v0
	v_mov_b32_e32 v67, v0
	v_mov_b32_e32 v68, v0
	v_mov_b32_e32 v69, v0
	v_mov_b32_e32 v70, v0
	v_mov_b32_e32 v71, v0
	v_mov_b32_e32 v72, v0
	v_mov_b32_e32 v73, v0
	v_mov_b32_e32 v74, v0
	v_mov_b32_e32 v75, v0
	v_mov_b32_e32 v76, v0
	v_mov_b32_e32 v77, v0
	v_mov_b32_e32 v78, v0
	v_mov_b32_e32 v79, v0
	v_mov_b32_e32 v80, v0
	v_mov_b32_e32 v81, v0
	v_mov_b32_e32 v82, v0
	v_mov_b32_e32 v83, v0
	v_mov_b32_e32 v84, v0
	v_mov_b32_e32 v85, v0
	v_mov_b32_e32 v86, v0
	v_mov_b32_e32 v87, v0
	v_mov_b32_e32 v88, v0
	v_mov_b32_e32 v89, v0
	v_mov_b32_e32 v90, v0
	v_mov_b32_e32 v91, v0
	v_mov_b32_e32 v92, v0
	v_mov_b32_e32 v93, v0
	v_mov_b32_e32 v94, v0
	v_mov_b32_e32 v95, v0
	v_mov_b32_e32 v96, v0
	v_mov_b32_e32 v97, v0
	v_mov_b32_e32 v98, v0
	v_mov_b32_e32 v99, v0
	v_mov_b32_e32 v100, v0
	v_mov_b32_e32 v101, v0
	v_mov_b32_e32 v102, v0
	v_mov_b32_e32 v103, v0
	v_mov_b32_e32 v104, v0
	v_mov_b32_e32 v105, v0
	v_mov_b32_e32 v106, v0
	v_mov_b32_e32 v107, v0
	v_mov_b32_e32 v108, v0
	v_mov_b32_e32 v109, v0
	v_mov_b32_e32 v110, v0
	v_mov_b32_e32 v111, v0
	v_mov_b32_e32 v112, v0
	v_mov_b32_e32 v113, v0
	v_mov_b32_e32 v114, v0
	v_mov_b32_e32 v115, v0
	v_mov_b32_e32 v116, v0
	v_mov_b32_e32 v117, v0
	v_mov_b32_e32 v118, v0
	v_mov_b32_e32 v119, v0
	v_mov_b32_e32 v120, v0
	v_mov_b32_e32 v121, v0
	v_mov_b32_e32 v122, v0
	v_mov_b32_e32 v123, v0
	v_mov_b32_e32 v124, v0
	v_mov_b32_e32 v125, v0
	v_mov_b32_e32 v126, v0
	v_mov_b32_e32 v127, v0
	.p2align	6

.LBB0_1392:
	s_and_b32 s13, s13, 3
	s_lshl_b32 s59, s12, 6
	s_lshl_b32 s17, s12, 13
	s_lshl_b32 s60, s13, 5
	s_lshl_b32 s20, s13, 12
	s_mov_b64 s[12:13], 0x80
	s_add_i32 m0, s54, 0x18000
	v_lshl_add_u64 v[6:7], v[6:7], 0, s[12:13]
	s_waitcnt vmcnt(4)
	s_barrier
	global_load_lds_dwordx4 v[6:7], off
	v_lshl_add_u64 v[4:5], v[4:5], 0, s[12:13]
	s_add_i32 m0, s54, 0x1a000
	s_add_i32 s61, s54, 0x8000
	s_add_i32 s62, s54, 0xa000
	global_load_lds_dwordx4 v[4:5], off
	v_lshl_add_u64 v[2:3], v[2:3], 0, s[12:13]
	s_mov_b32 m0, s61
	s_add_u32 s18, s34, 0x40080
	global_load_lds_dwordx4 v[2:3], off
	v_lshl_add_u64 v[0:1], v[0:1], 0, s[12:13]
	s_mov_b32 m0, s62
	s_addc_u32 s19, s35, 0
	global_load_lds_dwordx4 v[0:1], off
	s_add_i32 m0, s54, 0x1c000
	v_lshl_add_u64 v[0:1], s[18:19], 0, v[130:131]
	global_load_lds_dwordx4 v[0:1], off
	v_lshl_add_u64 v[0:1], s[18:19], 0, v[128:129]
	s_add_i32 m0, s54, 0x1e000
	v_and_b32_e32 v142, 15, v8
	global_load_lds_dwordx4 v[0:1], off
	v_bfe_u32 v0, v8, 4, 2
	v_lshlrev_b32_e32 v1, 4, v0
	v_lshlrev_b32_e32 v2, 2, v8
	v_lshlrev_b32_e32 v144, 2, v0
	v_lshlrev_b32_e32 v0, 14, v9
	v_lshl_or_b32 v1, v142, 6, v1
	v_and_b32_e32 v2, 32, v2
	v_and_b32_e32 v0, 0xffff8000, v0
	v_bitop3_b32 v3, v1, s17, v2 bitop3:0xde
	v_bitop3_b32 v143, v1, s20, v2 bitop3:0xde
	v_lshl_add_u32 v0, v10, 11, v0
	v_and_b32_e32 v1, 1, v9
	v_lshl_or_b32 v0, v1, 6, v0
	v_lshl_add_u32 v134, v11, 1, v0
	v_lshlrev_b32_e32 v0, 14, v12
	s_ashr_i32 s63, s42, 31
	v_and_b32_e32 v0, 0xffff8000, v0
	s_sext_i32_i8 s31, s16
	s_waitcnt vmcnt(6)
	s_add_u32 s16, s10, 0x779c000
	v_lshl_add_u32 v0, v13, 11, v0
	v_and_b32_e32 v1, 1, v12
	s_addc_u32 s17, s11, 0
	v_lshl_or_b32 v0, v1, 6, v0
	s_add_i32 s65, 0, 0x10000
	s_add_i32 s66, 0, 0x14000
	s_mov_b32 s64, s42
	v_mov_b32_e32 v135, v133
	v_lshl_add_u32 v136, v14, 1, v0
	v_mov_b32_e32 v137, v133
	v_mov_b64_e32 v[138:139], 0x300
	v_mov_b64_e32 v[140:141], 0x2ff
	v_add_u32_e32 v145, s65, v143
	v_add_u32_e32 v146, 0, v3
	v_add_u32_e32 v147, s66, v143
	s_mov_b64 s[18:19], 0x1000
	s_mov_b64 s[20:21], 0x1800
	v_mov_b32_e32 v148, 0x90
	s_barrier
	.p2align	6

.LBB0_1395:
	s_ashr_i32 s25, s24, 31
	v_cmp_lt_i64_e32 vcc, s[26:27], v[138:139]
	s_lshl_b64 s[26:27], s[24:25], 19
	s_add_u32 s26, s51, s26
	s_addc_u32 s27, s52, s27
	s_and_b64 s[28:29], vcc, exec
	s_cselect_b32 s25, s27, s37
	s_cselect_b32 s67, s26, s36
	s_ashr_i32 s23, s22, 31
	s_lshl_b64 s[28:29], s[22:23], 19
	s_add_u32 s28, s47, s28
	s_addc_u32 s29, s50, s29
	s_and_b64 s[40:41], vcc, exec
	s_cselect_b32 s23, s29, s35
	s_cselect_b32 s68, s28, s34
	s_add_u32 s69, s34, 0x100
	s_addc_u32 s70, s35, 0
	s_add_u32 s34, s36, 0x40080
	v_mov_b32_e32 v0, 0
	s_addc_u32 s35, s37, 0
	s_mov_b32 s71, -2
	v_mov_b32_e32 v1, v0
	v_mov_b32_e32 v2, v0
	v_mov_b32_e32 v3, v0
	v_mov_b32_e32 v4, v0
	v_mov_b32_e32 v5, v0
	v_mov_b32_e32 v6, v0
	v_mov_b32_e32 v7, v0
	v_mov_b32_e32 v8, v0
	v_mov_b32_e32 v9, v0
	v_mov_b32_e32 v10, v0
	v_mov_b32_e32 v11, v0
	v_mov_b32_e32 v12, v0
	v_mov_b32_e32 v13, v0
	v_mov_b32_e32 v14, v0
	v_mov_b32_e32 v15, v0
	v_mov_b32_e32 v16, v0
	v_mov_b32_e32 v17, v0
	v_mov_b32_e32 v18, v0
	v_mov_b32_e32 v19, v0
	v_mov_b32_e32 v20, v0
	v_mov_b32_e32 v21, v0
	v_mov_b32_e32 v22, v0
	v_mov_b32_e32 v23, v0
	v_mov_b32_e32 v24, v0
	v_mov_b32_e32 v25, v0
	v_mov_b32_e32 v26, v0
	v_mov_b32_e32 v27, v0
	v_mov_b32_e32 v28, v0
	v_mov_b32_e32 v29, v0
	v_mov_b32_e32 v30, v0
	v_mov_b32_e32 v31, v0
	v_mov_b32_e32 v32, v0
	v_mov_b32_e32 v33, v0
	v_mov_b32_e32 v34, v0
	v_mov_b32_e32 v35, v0
	v_mov_b32_e32 v36, v0
	v_mov_b32_e32 v37, v0
	v_mov_b32_e32 v38, v0
	v_mov_b32_e32 v39, v0
	v_mov_b32_e32 v40, v0
	v_mov_b32_e32 v41, v0
	v_mov_b32_e32 v42, v0
	v_mov_b32_e32 v43, v0
	v_mov_b32_e32 v44, v0
	v_mov_b32_e32 v45, v0
	v_mov_b32_e32 v46, v0
	v_mov_b32_e32 v47, v0
	v_mov_b32_e32 v48, v0
	v_mov_b32_e32 v49, v0
	v_mov_b32_e32 v50, v0
	v_mov_b32_e32 v51, v0
	v_mov_b32_e32 v52, v0
	v_mov_b32_e32 v53, v0
	v_mov_b32_e32 v54, v0
	v_mov_b32_e32 v55, v0
	v_mov_b32_e32 v56, v0
	v_mov_b32_e32 v57, v0
	v_mov_b32_e32 v58, v0
	v_mov_b32_e32 v59, v0
	v_mov_b32_e32 v60, v0
	v_mov_b32_e32 v61, v0
	v_mov_b32_e32 v62, v0
	v_mov_b32_e32 v63, v0
	v_mov_b32_e32 v64, v0
	v_mov_b32_e32 v65, v0
	v_mov_b32_e32 v66, v0
	v_mov_b32_e32 v67, v0
	v_mov_b32_e32 v68, v0
	v_mov_b32_e32 v69, v0
	v_mov_b32_e32 v70, v0
	v_mov_b32_e32 v71, v0
	v_mov_b32_e32 v72, v0
	v_mov_b32_e32 v73, v0
	v_mov_b32_e32 v74, v0
	v_mov_b32_e32 v75, v0
	v_mov_b32_e32 v76, v0
	v_mov_b32_e32 v77, v0
	v_mov_b32_e32 v78, v0
	v_mov_b32_e32 v79, v0
	v_mov_b32_e32 v80, v0
	v_mov_b32_e32 v81, v0
	v_mov_b32_e32 v82, v0
	v_mov_b32_e32 v83, v0
	v_mov_b32_e32 v84, v0
	v_mov_b32_e32 v85, v0
	v_mov_b32_e32 v86, v0
	v_mov_b32_e32 v87, v0
	v_mov_b32_e32 v88, v0
	v_mov_b32_e32 v89, v0
	v_mov_b32_e32 v90, v0
	v_mov_b32_e32 v91, v0
	v_mov_b32_e32 v92, v0
	v_mov_b32_e32 v93, v0
	v_mov_b32_e32 v94, v0
	v_mov_b32_e32 v95, v0
	v_mov_b32_e32 v96, v0
	v_mov_b32_e32 v97, v0
	v_mov_b32_e32 v98, v0
	v_mov_b32_e32 v99, v0
	v_mov_b32_e32 v100, v0
	v_mov_b32_e32 v101, v0
	v_mov_b32_e32 v102, v0
	v_mov_b32_e32 v103, v0
	v_mov_b32_e32 v104, v0
	v_mov_b32_e32 v105, v0
	v_mov_b32_e32 v106, v0
	v_mov_b32_e32 v107, v0
	v_mov_b32_e32 v108, v0
	v_mov_b32_e32 v109, v0
	v_mov_b32_e32 v110, v0
	v_mov_b32_e32 v111, v0
	v_mov_b32_e32 v112, v0
	v_mov_b32_e32 v113, v0
	v_mov_b32_e32 v114, v0
	v_mov_b32_e32 v115, v0
	v_mov_b32_e32 v116, v0
	v_mov_b32_e32 v117, v0
	v_mov_b32_e32 v118, v0
	v_mov_b32_e32 v119, v0
	v_mov_b32_e32 v120, v0
	v_mov_b32_e32 v121, v0
	v_mov_b32_e32 v122, v0
	v_mov_b32_e32 v123, v0
	v_mov_b32_e32 v124, v0
	v_mov_b32_e32 v125, v0
	v_mov_b32_e32 v126, v0
	v_mov_b32_e32 v127, v0
	.p2align	6

.LBB0_1456:
	s_and_b32 s26, s16, 3
	s_mov_b64 s[16:17], 0x80
	s_add_i32 m0, s64, 0x18000
	v_lshl_add_u64 v[2:3], v[2:3], 0, s[16:17]
	s_lshl_b32 s27, s13, 13
	s_lshl_b32 s28, s26, 12
	s_waitcnt vmcnt(4)
	s_barrier
	global_load_lds_dwordx4 v[2:3], off
	s_add_i32 m0, s64, 0x1a000
	s_add_u32 s18, s54, 0x8000
	v_lshl_add_u64 v[0:1], v[0:1], 0, s[16:17]
	s_addc_u32 s19, s55, 0
	s_add_i32 s68, s64, 0x8000
	global_load_lds_dwordx4 v[0:1], off
	v_lshl_add_u64 v[0:1], s[18:19], 0, v[134:135]
	s_mov_b32 m0, s68
	s_add_i32 s69, s64, 0xa000
	global_load_lds_dwordx4 v[0:1], off
	v_lshl_add_u64 v[0:1], s[18:19], 0, v[130:131]
	s_add_u32 s18, s52, 0x100080
	s_mov_b32 m0, s69
	s_addc_u32 s19, s53, 0
	global_load_lds_dwordx4 v[0:1], off
	s_add_i32 m0, s64, 0x1c000
	v_lshl_add_u64 v[0:1], s[18:19], 0, v[132:133]
	global_load_lds_dwordx4 v[0:1], off
	v_lshl_add_u64 v[0:1], s[18:19], 0, v[128:129]
	s_add_i32 m0, s64, 0x1e000
	s_ashr_i32 s70, s42, 31
	global_load_lds_dwordx4 v[0:1], off
	v_bfe_u32 v1, v4, 4, 2
	v_and_b32_e32 v0, 15, v4
	v_lshlrev_b32_e32 v2, 4, v1
	v_lshl_or_b32 v152, s13, 6, v0
	v_lshl_or_b32 v0, v0, 6, v2
	v_lshlrev_b32_e32 v2, 2, v4
	v_and_b32_e32 v2, 32, v2
	v_bitop3_b32 v3, v0, s27, v2 bitop3:0xde
	v_bitop3_b32 v153, v0, s28, v2 bitop3:0xde
	v_lshlrev_b32_e32 v0, 2, v1
	v_lshl_or_b32 v154, s26, 5, v0
	v_lshlrev_b32_e32 v0, 10, v5
	v_and_b32_e32 v0, 0xfffff800, v0
	v_lshl_add_u32 v0, v6, 7, v0
	v_and_b32_e32 v1, 1, v5
	v_lshl_or_b32 v0, v1, 6, v0
	v_lshl_add_u32 v136, v7, 1, v0
	v_lshlrev_b32_e32 v0, 10, v8
	v_and_b32_e32 v0, 0xfffff800, v0
	s_waitcnt vmcnt(6)
	s_add_u32 s72, s22, 0x780000
	v_lshl_add_u32 v0, v9, 7, v0
	v_and_b32_e32 v1, 1, v8
	s_addc_u32 s73, s23, 0
	v_lshl_or_b32 v0, v1, 6, v0
	s_add_i32 s74, 0, 0x10000
	s_add_i32 s75, 0, 0x14000
	s_sext_i32_i8 s81, s12
	s_mov_b32 s71, s42
	v_mov_b32_e32 v137, v133
	v_lshl_add_u32 v138, v10, 1, v0
	v_mov_b32_e32 v139, v133
	v_mov_b64_e32 v[140:141], 0xc0
	v_mov_b64_e32 v[142:143], 0xbf
	v_add_u32_e32 v155, s74, v153
	v_add_u32_e32 v156, 0, v3
	v_add_u32_e32 v157, s75, v153
	s_mov_b64 s[18:19], 0x80000
	s_mov_b32 s76, 0x80000
	s_mov_b64 s[26:27], 0x90000
	s_mov_b32 s77, 0x90000
	s_mov_b64 s[28:29], 0xa0000
	s_mov_b32 s78, 0xa0000
	s_mov_b64 s[30:31], 0xb0000
	s_mov_b32 s79, 0xb0000
	s_mov_b32 s80, 0
	s_barrier
	.p2align	6

.LBB0_1459:
	s_ashr_i32 s37, s36, 31
	v_cmp_lt_i64_e32 vcc, s[40:41], v[140:141]
	s_lshl_b64 s[40:41], s[36:37], 21
	s_add_u32 s40, s61, s40
	s_addc_u32 s41, s62, s41
	s_and_b64 s[50:51], vcc, exec
	s_cselect_b32 s37, s41, s55
	s_cselect_b32 s82, s40, s54
	s_ashr_i32 s35, s34, 31
	s_lshl_b64 s[50:51], s[34:35], 21
	s_add_u32 s50, s45, s50
	s_addc_u32 s51, s47, s51
	s_and_b64 s[56:57], vcc, exec
	s_cselect_b32 s35, s51, s53
	s_cselect_b32 s83, s50, s52
	s_add_u32 s84, s52, 0x100
	s_addc_u32 s85, s53, 0
	s_add_u32 s52, s54, 0xc000
	v_mov_b32_e32 v0, 0
	s_addc_u32 s53, s55, 0
	s_mov_b32 s86, -2
	v_mov_b32_e32 v1, v0
	v_mov_b32_e32 v2, v0
	v_mov_b32_e32 v3, v0
	v_mov_b32_e32 v4, v0
	v_mov_b32_e32 v5, v0
	v_mov_b32_e32 v6, v0
	v_mov_b32_e32 v7, v0
	v_mov_b32_e32 v16, v0
	v_mov_b32_e32 v17, v0
	v_mov_b32_e32 v18, v0
	v_mov_b32_e32 v19, v0
	v_mov_b32_e32 v20, v0
	v_mov_b32_e32 v21, v0
	v_mov_b32_e32 v22, v0
	v_mov_b32_e32 v23, v0
	v_mov_b32_e32 v32, v0
	v_mov_b32_e32 v33, v0
	v_mov_b32_e32 v34, v0
	v_mov_b32_e32 v35, v0
	v_mov_b32_e32 v36, v0
	v_mov_b32_e32 v37, v0
	v_mov_b32_e32 v38, v0
	v_mov_b32_e32 v39, v0
	v_mov_b32_e32 v48, v0
	v_mov_b32_e32 v49, v0
	v_mov_b32_e32 v50, v0
	v_mov_b32_e32 v51, v0
	v_mov_b32_e32 v52, v0
	v_mov_b32_e32 v53, v0
	v_mov_b32_e32 v54, v0
	v_mov_b32_e32 v55, v0
	v_mov_b32_e32 v8, v0
	v_mov_b32_e32 v9, v0
	v_mov_b32_e32 v10, v0
	v_mov_b32_e32 v11, v0
	v_mov_b32_e32 v12, v0
	v_mov_b32_e32 v13, v0
	v_mov_b32_e32 v14, v0
	v_mov_b32_e32 v15, v0
	v_mov_b32_e32 v24, v0
	v_mov_b32_e32 v25, v0
	v_mov_b32_e32 v26, v0
	v_mov_b32_e32 v27, v0
	v_mov_b32_e32 v28, v0
	v_mov_b32_e32 v29, v0
	v_mov_b32_e32 v30, v0
	v_mov_b32_e32 v31, v0
	v_mov_b32_e32 v40, v0
	v_mov_b32_e32 v41, v0
	v_mov_b32_e32 v42, v0
	v_mov_b32_e32 v43, v0
	v_mov_b32_e32 v44, v0
	v_mov_b32_e32 v45, v0
	v_mov_b32_e32 v46, v0
	v_mov_b32_e32 v47, v0
	v_mov_b32_e32 v56, v0
	v_mov_b32_e32 v57, v0
	v_mov_b32_e32 v58, v0
	v_mov_b32_e32 v59, v0
	v_mov_b32_e32 v60, v0
	v_mov_b32_e32 v61, v0
	v_mov_b32_e32 v62, v0
	v_mov_b32_e32 v63, v0
	v_mov_b32_e32 v64, v0
	v_mov_b32_e32 v65, v0
	v_mov_b32_e32 v66, v0
	v_mov_b32_e32 v67, v0
	v_mov_b32_e32 v68, v0
	v_mov_b32_e32 v69, v0
	v_mov_b32_e32 v70, v0
	v_mov_b32_e32 v71, v0
	v_mov_b32_e32 v80, v0
	v_mov_b32_e32 v81, v0
	v_mov_b32_e32 v82, v0
	v_mov_b32_e32 v83, v0
	v_mov_b32_e32 v84, v0
	v_mov_b32_e32 v85, v0
	v_mov_b32_e32 v86, v0
	v_mov_b32_e32 v87, v0
	v_mov_b32_e32 v96, v0
	v_mov_b32_e32 v97, v0
	v_mov_b32_e32 v98, v0
	v_mov_b32_e32 v99, v0
	v_mov_b32_e32 v100, v0
	v_mov_b32_e32 v101, v0
	v_mov_b32_e32 v102, v0
	v_mov_b32_e32 v103, v0
	v_mov_b32_e32 v112, v0
	v_mov_b32_e32 v113, v0
	v_mov_b32_e32 v114, v0
	v_mov_b32_e32 v115, v0
	v_mov_b32_e32 v116, v0
	v_mov_b32_e32 v117, v0
	v_mov_b32_e32 v118, v0
	v_mov_b32_e32 v119, v0
	v_mov_b32_e32 v72, v0
	v_mov_b32_e32 v73, v0
	v_mov_b32_e32 v74, v0
	v_mov_b32_e32 v75, v0
	v_mov_b32_e32 v76, v0
	v_mov_b32_e32 v77, v0
	v_mov_b32_e32 v78, v0
	v_mov_b32_e32 v79, v0
	v_mov_b32_e32 v88, v0
	v_mov_b32_e32 v89, v0
	v_mov_b32_e32 v90, v0
	v_mov_b32_e32 v91, v0
	v_mov_b32_e32 v92, v0
	v_mov_b32_e32 v93, v0
	v_mov_b32_e32 v94, v0
	v_mov_b32_e32 v95, v0
	v_mov_b32_e32 v104, v0
	v_mov_b32_e32 v105, v0
	v_mov_b32_e32 v106, v0
	v_mov_b32_e32 v107, v0
	v_mov_b32_e32 v108, v0
	v_mov_b32_e32 v109, v0
	v_mov_b32_e32 v110, v0
	v_mov_b32_e32 v111, v0
	v_mov_b32_e32 v120, v0
	v_mov_b32_e32 v121, v0
	v_mov_b32_e32 v122, v0
	v_mov_b32_e32 v123, v0
	v_mov_b32_e32 v124, v0
	v_mov_b32_e32 v125, v0
	v_mov_b32_e32 v126, v0
	v_mov_b32_e32 v127, v0
	.p2align	6

.LBB0_1822:
	s_and_b32 s28, s24, 3
	s_mov_b64 s[24:25], 0x80
	s_add_i32 m0, s48, 0x18000
	v_lshl_add_u64 v[6:7], v[6:7], 0, s[24:25]
	s_lshl_b32 s29, s13, 13
	s_lshl_b32 s30, s28, 12
	s_waitcnt vmcnt(4)
	s_barrier
	global_load_lds_dwordx4 v[6:7], off
	v_lshl_add_u64 v[4:5], v[4:5], 0, s[24:25]
	s_add_i32 m0, s48, 0x1a000
	s_add_i32 s78, s48, 0x8000
	s_add_i32 s79, s48, 0xa000
	global_load_lds_dwordx4 v[4:5], off
	v_lshl_add_u64 v[2:3], v[2:3], 0, s[24:25]
	s_mov_b32 m0, s78
	s_add_u32 s26, s54, 0x10080
	global_load_lds_dwordx4 v[2:3], off
	v_lshl_add_u64 v[0:1], v[0:1], 0, s[24:25]
	s_mov_b32 m0, s79
	s_addc_u32 s27, s55, 0
	global_load_lds_dwordx4 v[0:1], off
	s_add_i32 m0, s48, 0x1c000
	v_lshl_add_u64 v[0:1], s[26:27], 0, v[132:133]
	global_load_lds_dwordx4 v[0:1], off
	v_lshl_add_u64 v[0:1], s[26:27], 0, v[128:129]
	s_add_i32 m0, s48, 0x1e000
	s_ashr_i32 s80, s42, 31
	global_load_lds_dwordx4 v[0:1], off
	v_bfe_u32 v1, v8, 4, 2
	v_and_b32_e32 v0, 15, v8
	v_lshlrev_b32_e32 v2, 4, v1
	v_lshl_or_b32 v146, s13, 6, v0
	v_lshl_or_b32 v0, v0, 6, v2
	v_lshlrev_b32_e32 v2, 2, v8
	v_and_b32_e32 v2, 32, v2
	s_waitcnt vmcnt(6)
	s_add_u32 s82, s14, 0x780000
	v_bitop3_b32 v3, v0, s29, v2 bitop3:0xde
	v_bitop3_b32 v147, v0, s30, v2 bitop3:0xde
	v_lshlrev_b32_e32 v0, 2, v1
	s_addc_u32 s83, s15, 0
	s_add_i32 s84, 0, 0x10000
	s_add_i32 s85, 0, 0x14000
	s_sext_i32_i8 s91, s12
	s_mov_b32 s81, s42
	v_lshl_or_b32 v148, s28, 5, v0
	v_mov_b64_e32 v[136:137], 0xc0
	v_mov_b64_e32 v[138:139], 0xbf
	v_add_u32_e32 v149, s84, v147
	v_add_u32_e32 v150, 0, v3
	v_add_u32_e32 v151, s85, v147
	s_mov_b64 s[26:27], 0x80000
	s_mov_b32 s86, 0x80000
	s_mov_b64 s[28:29], 0x90000
	s_mov_b32 s87, 0x90000
	s_mov_b64 s[30:31], 0xa0000
	s_mov_b32 s88, 0xa0000
	s_mov_b64 s[34:35], 0xb0000
	s_mov_b32 s89, 0xb0000
	s_mov_b32 s90, 0
	s_barrier
	.p2align	6
.LBB0_1823:
	s_add_i32 s90, s90, 1
	s_mul_i32 s12, s90, s80
	s_mul_hi_u32 s13, s90, s81
	s_add_i32 s13, s13, s12
	s_mul_i32 s12, s90, s81
	s_add_u32 s52, s12, s2
	s_addc_u32 s53, s13, s3
	v_cmp_gt_i64_e64 s[12:13], s[52:53], v[138:139]
	s_and_b64 vcc, exec, s[12:13]
	s_cbranch_vccnz .LBB0_1830
	s_ashr_i32 s33, s52, 31
	s_lshr_b32 s33, s33, 29
	s_add_i32 s33, s52, s33
	s_ashr_i32 s36, s33, 3
	s_and_b32 s33, s33, -8
	s_sub_i32 s33, s52, s33
	s_lshr_b32 s37, s33, 31
	s_or_b32 s37, s37, 24
	s_mul_i32 s33, s37, s33
	s_add_i32 s33, s33, s36
	s_ashr_i32 s36, s33, 31
	s_lshr_b32 s36, s36, 27
	s_add_i32 s36, s33, s36
	s_ashr_i32 s37, s36, 5
	s_lshl_b32 s37, s37, 3
	s_sub_i32 s40, 48, s37
	s_min_i32 s40, s40, 8
	s_abs_i32 s41, s40
	v_cvt_f32_u32_e32 v0, s41
	s_sub_i32 s51, 0, s41
	s_andn2_b32 s36, s36, 31
	s_sub_i32 s33, s33, s36
	v_rcp_iflag_f32_e32 v0, v0
	s_abs_i32 s36, s33
	s_xor_b32 s50, s33, s40
	s_ashr_i32 s50, s50, 31
	v_mul_f32_e32 v0, 0x4f7ffffe, v0
	v_cvt_u32_f32_e32 v0, v0
	s_nop 0
	v_readfirstlane_b32 s58, v0
	s_mul_i32 s51, s51, s58
	s_mul_hi_u32 s51, s58, s51
	s_add_i32 s58, s58, s51
	s_mul_hi_u32 s51, s36, s58
	s_mul_i32 s58, s51, s41
	s_sub_i32 s36, s36, s58
	s_add_i32 s59, s51, 1
	s_sub_i32 s58, s36, s41
	s_cmp_ge_u32 s36, s41
	s_cselect_b32 s51, s59, s51
	s_cselect_b32 s36, s58, s36
	s_add_i32 s58, s51, 1
	s_cmp_ge_u32 s36, s41
	s_cselect_b32 s36, s58, s51
	s_xor_b32 s36, s36, s50
	s_sub_i32 s36, s36, s50
	s_mul_i32 s40, s36, s40
	s_sub_i32 s33, s33, s40
	s_add_i32 s40, s33, s37
	s_andn2_b64 vcc, exec, s[12:13]
	s_mov_b64 s[50:51], -1
	s_cbranch_vccz .LBB0_1831
	.p2align	6
.LBB0_1825:
	s_andn2_b64 vcc, exec, s[50:51]
	s_mov_b64 s[50:51], s[56:57]
	s_cbranch_vccnz .LBB0_1827
	.p2align	6

.LBB0_1827:
	v_cmp_lt_i64_e32 vcc, s[52:53], v[136:137]
	s_lshl_b64 s[52:53], s[36:37], 17
	s_add_u32 s52, s47, s52
	s_addc_u32 s53, s72, s53
	s_and_b64 s[58:59], vcc, exec
	v_mov_b32_e32 v0, 0
	s_cselect_b32 s37, s53, s55
	s_cselect_b32 s41, s52, s54
	s_mov_b32 s62, 0
	s_mov_b64 s[58:59], -1
	s_mov_b64 s[60:61], 0
	v_mov_b32_e32 v1, v0
	v_mov_b32_e32 v2, v0
	v_mov_b32_e32 v3, v0
	v_mov_b32_e32 v4, v0
	v_mov_b32_e32 v5, v0
	v_mov_b32_e32 v6, v0
	v_mov_b32_e32 v7, v0
	v_mov_b32_e32 v8, v0
	v_mov_b32_e32 v9, v0
	v_mov_b32_e32 v10, v0
	v_mov_b32_e32 v11, v0
	v_mov_b32_e32 v12, v0
	v_mov_b32_e32 v13, v0
	v_mov_b32_e32 v14, v0
	v_mov_b32_e32 v15, v0
	v_mov_b32_e32 v16, v0
	v_mov_b32_e32 v17, v0
	v_mov_b32_e32 v18, v0
	v_mov_b32_e32 v19, v0
	v_mov_b32_e32 v20, v0
	v_mov_b32_e32 v21, v0
	v_mov_b32_e32 v22, v0
	v_mov_b32_e32 v23, v0
	v_mov_b32_e32 v24, v0
	v_mov_b32_e32 v25, v0
	v_mov_b32_e32 v26, v0
	v_mov_b32_e32 v27, v0
	v_mov_b32_e32 v28, v0
	v_mov_b32_e32 v29, v0
	v_mov_b32_e32 v30, v0
	v_mov_b32_e32 v31, v0
	v_mov_b32_e32 v32, v0
	v_mov_b32_e32 v33, v0
	v_mov_b32_e32 v34, v0
	v_mov_b32_e32 v35, v0
	v_mov_b32_e32 v36, v0
	v_mov_b32_e32 v37, v0
	v_mov_b32_e32 v38, v0
	v_mov_b32_e32 v39, v0
	v_mov_b32_e32 v40, v0
	v_mov_b32_e32 v41, v0
	v_mov_b32_e32 v42, v0
	v_mov_b32_e32 v43, v0
	v_mov_b32_e32 v44, v0
	v_mov_b32_e32 v45, v0
	v_mov_b32_e32 v46, v0
	v_mov_b32_e32 v47, v0
	v_mov_b32_e32 v48, v0
	v_mov_b32_e32 v49, v0
	v_mov_b32_e32 v50, v0
	v_mov_b32_e32 v51, v0
	v_mov_b32_e32 v52, v0
	v_mov_b32_e32 v53, v0
	v_mov_b32_e32 v54, v0
	v_mov_b32_e32 v55, v0
	v_mov_b32_e32 v56, v0
	v_mov_b32_e32 v57, v0
	v_mov_b32_e32 v58, v0
	v_mov_b32_e32 v59, v0
	v_mov_b32_e32 v60, v0
	v_mov_b32_e32 v61, v0
	v_mov_b32_e32 v62, v0
	v_mov_b32_e32 v63, v0
	v_mov_b32_e32 v64, v0
	v_mov_b32_e32 v65, v0
	v_mov_b32_e32 v66, v0
	v_mov_b32_e32 v67, v0
	v_mov_b32_e32 v68, v0
	v_mov_b32_e32 v69, v0
	v_mov_b32_e32 v70, v0
	v_mov_b32_e32 v71, v0
	v_mov_b32_e32 v72, v0
	v_mov_b32_e32 v73, v0
	v_mov_b32_e32 v74, v0
	v_mov_b32_e32 v75, v0
	v_mov_b32_e32 v76, v0
	v_mov_b32_e32 v77, v0
	v_mov_b32_e32 v78, v0
	v_mov_b32_e32 v79, v0
	v_mov_b32_e32 v80, v0
	v_mov_b32_e32 v81, v0
	v_mov_b32_e32 v82, v0
	v_mov_b32_e32 v83, v0
	v_mov_b32_e32 v84, v0
	v_mov_b32_e32 v85, v0
	v_mov_b32_e32 v86, v0
	v_mov_b32_e32 v87, v0
	v_mov_b32_e32 v88, v0
	v_mov_b32_e32 v89, v0
	v_mov_b32_e32 v90, v0
	v_mov_b32_e32 v91, v0
	v_mov_b32_e32 v92, v0
	v_mov_b32_e32 v93, v0
	v_mov_b32_e32 v94, v0
	v_mov_b32_e32 v95, v0
	v_mov_b32_e32 v96, v0
	v_mov_b32_e32 v97, v0
	v_mov_b32_e32 v98, v0
	v_mov_b32_e32 v99, v0
	v_mov_b32_e32 v100, v0
	v_mov_b32_e32 v101, v0
	v_mov_b32_e32 v102, v0
	v_mov_b32_e32 v103, v0
	v_mov_b32_e32 v104, v0
	v_mov_b32_e32 v105, v0
	v_mov_b32_e32 v106, v0
	v_mov_b32_e32 v107, v0
	v_mov_b32_e32 v108, v0
	v_mov_b32_e32 v109, v0
	v_mov_b32_e32 v110, v0
	v_mov_b32_e32 v111, v0
	v_mov_b32_e32 v112, v0
	v_mov_b32_e32 v113, v0
	v_mov_b32_e32 v114, v0
	v_mov_b32_e32 v115, v0
	v_mov_b32_e32 v116, v0
	v_mov_b32_e32 v117, v0
	v_mov_b32_e32 v118, v0
	v_mov_b32_e32 v119, v0
	v_mov_b32_e32 v120, v0
	v_mov_b32_e32 v121, v0
	v_mov_b32_e32 v122, v0
	v_mov_b32_e32 v123, v0
	v_mov_b32_e32 v124, v0
	v_mov_b32_e32 v125, v0
	v_mov_b32_e32 v126, v0
	v_mov_b32_e32 v127, v0
	.p2align	6

.LBB0_1981:
	s_and_b32 s13, s13, 3
	s_lshl_b32 s57, s12, 6
	s_lshl_b32 s15, s12, 13
	s_lshl_b32 s58, s13, 5
	s_lshl_b32 s18, s13, 12
	s_mov_b64 s[12:13], 0x80
	s_add_i32 m0, s52, 0x18000
	v_lshl_add_u64 v[6:7], v[6:7], 0, s[12:13]
	s_waitcnt vmcnt(4)
	s_barrier
	global_load_lds_dwordx4 v[6:7], off
	v_lshl_add_u64 v[4:5], v[4:5], 0, s[12:13]
	s_add_i32 m0, s52, 0x1a000
	s_add_i32 s59, s52, 0x8000
	s_add_i32 s60, s52, 0xa000
	global_load_lds_dwordx4 v[4:5], off
	v_lshl_add_u64 v[2:3], v[2:3], 0, s[12:13]
	s_mov_b32 m0, s59
	s_add_u32 s16, s30, 0x40080
	global_load_lds_dwordx4 v[2:3], off
	v_lshl_add_u64 v[0:1], v[0:1], 0, s[12:13]
	s_mov_b32 m0, s60
	s_addc_u32 s17, s31, 0
	global_load_lds_dwordx4 v[0:1], off
	s_add_i32 m0, s52, 0x1c000
	v_lshl_add_u64 v[0:1], s[16:17], 0, v[130:131]
	global_load_lds_dwordx4 v[0:1], off
	v_lshl_add_u64 v[0:1], s[16:17], 0, v[128:129]
	s_add_i32 m0, s52, 0x1e000
	v_and_b32_e32 v142, 15, v8
	global_load_lds_dwordx4 v[0:1], off
	v_bfe_u32 v0, v8, 4, 2
	v_lshlrev_b32_e32 v1, 4, v0
	v_lshlrev_b32_e32 v2, 2, v8
	v_lshlrev_b32_e32 v144, 2, v0
	v_lshlrev_b32_e32 v0, 14, v9
	v_lshl_or_b32 v1, v142, 6, v1
	v_and_b32_e32 v2, 32, v2
	v_and_b32_e32 v0, 0xffff8000, v0
	v_bitop3_b32 v3, v1, s15, v2 bitop3:0xde
	v_bitop3_b32 v143, v1, s18, v2 bitop3:0xde
	v_lshl_add_u32 v0, v10, 11, v0
	v_and_b32_e32 v1, 1, v9
	v_lshl_or_b32 v0, v1, 6, v0
	v_lshl_add_u32 v134, v11, 1, v0
	v_lshlrev_b32_e32 v0, 14, v12
	s_ashr_i32 s61, s42, 31
	v_and_b32_e32 v0, 0xffff8000, v0
	s_sext_i32_i8 s29, s14
	s_waitcnt vmcnt(6)
	s_add_u32 s14, s8, 0x779c000
	v_lshl_add_u32 v0, v13, 11, v0
	v_and_b32_e32 v1, 1, v12
	s_addc_u32 s15, s9, 0
	v_lshl_or_b32 v0, v1, 6, v0
	s_add_i32 s63, 0, 0x10000
	s_add_i32 s64, 0, 0x14000
	s_mov_b32 s62, s42
	v_mov_b32_e32 v135, v133
	v_lshl_add_u32 v136, v14, 1, v0
	v_mov_b32_e32 v137, v133
	v_mov_b64_e32 v[138:139], 0x300
	v_mov_b64_e32 v[140:141], 0x2ff
	v_add_u32_e32 v145, s63, v143
	v_add_u32_e32 v146, 0, v3
	v_add_u32_e32 v147, s64, v143
	s_mov_b64 s[16:17], 0x1000
	s_mov_b64 s[18:19], 0x1800
	v_mov_b32_e32 v148, 0x90
	s_barrier
	.p2align	6

.LBB0_1984:
	s_ashr_i32 s23, s22, 31
	v_cmp_lt_i64_e32 vcc, s[24:25], v[138:139]
	s_lshl_b64 s[24:25], s[22:23], 19
	s_add_u32 s24, s47, s24
	s_addc_u32 s25, s50, s25
	s_and_b64 s[26:27], vcc, exec
	s_cselect_b32 s23, s25, s35
	s_cselect_b32 s65, s24, s34
	s_ashr_i32 s21, s20, 31
	s_lshl_b64 s[26:27], s[20:21], 19
	s_add_u32 s26, s41, s26
	s_addc_u32 s27, s45, s27
	s_and_b64 s[36:37], vcc, exec
	s_cselect_b32 s21, s27, s31
	s_cselect_b32 s66, s26, s30
	s_add_u32 s67, s30, 0x100
	s_addc_u32 s68, s31, 0
	s_add_u32 s30, s34, 0x40080
	v_mov_b32_e32 v0, 0
	s_addc_u32 s31, s35, 0
	s_mov_b32 s69, -2
	v_mov_b32_e32 v1, v0
	v_mov_b32_e32 v2, v0
	v_mov_b32_e32 v3, v0
	v_mov_b32_e32 v4, v0
	v_mov_b32_e32 v5, v0
	v_mov_b32_e32 v6, v0
	v_mov_b32_e32 v7, v0
	v_mov_b32_e32 v8, v0
	v_mov_b32_e32 v9, v0
	v_mov_b32_e32 v10, v0
	v_mov_b32_e32 v11, v0
	v_mov_b32_e32 v12, v0
	v_mov_b32_e32 v13, v0
	v_mov_b32_e32 v14, v0
	v_mov_b32_e32 v15, v0
	v_mov_b32_e32 v16, v0
	v_mov_b32_e32 v17, v0
	v_mov_b32_e32 v18, v0
	v_mov_b32_e32 v19, v0
	v_mov_b32_e32 v20, v0
	v_mov_b32_e32 v21, v0
	v_mov_b32_e32 v22, v0
	v_mov_b32_e32 v23, v0
	v_mov_b32_e32 v24, v0
	v_mov_b32_e32 v25, v0
	v_mov_b32_e32 v26, v0
	v_mov_b32_e32 v27, v0
	v_mov_b32_e32 v28, v0
	v_mov_b32_e32 v29, v0
	v_mov_b32_e32 v30, v0
	v_mov_b32_e32 v31, v0
	v_mov_b32_e32 v32, v0
	v_mov_b32_e32 v33, v0
	v_mov_b32_e32 v34, v0
	v_mov_b32_e32 v35, v0
	v_mov_b32_e32 v36, v0
	v_mov_b32_e32 v37, v0
	v_mov_b32_e32 v38, v0
	v_mov_b32_e32 v39, v0
	v_mov_b32_e32 v40, v0
	v_mov_b32_e32 v41, v0
	v_mov_b32_e32 v42, v0
	v_mov_b32_e32 v43, v0
	v_mov_b32_e32 v44, v0
	v_mov_b32_e32 v45, v0
	v_mov_b32_e32 v46, v0
	v_mov_b32_e32 v47, v0
	v_mov_b32_e32 v48, v0
	v_mov_b32_e32 v49, v0
	v_mov_b32_e32 v50, v0
	v_mov_b32_e32 v51, v0
	v_mov_b32_e32 v52, v0
	v_mov_b32_e32 v53, v0
	v_mov_b32_e32 v54, v0
	v_mov_b32_e32 v55, v0
	v_mov_b32_e32 v56, v0
	v_mov_b32_e32 v57, v0
	v_mov_b32_e32 v58, v0
	v_mov_b32_e32 v59, v0
	v_mov_b32_e32 v60, v0
	v_mov_b32_e32 v61, v0
	v_mov_b32_e32 v62, v0
	v_mov_b32_e32 v63, v0
	v_mov_b32_e32 v64, v0
	v_mov_b32_e32 v65, v0
	v_mov_b32_e32 v66, v0
	v_mov_b32_e32 v67, v0
	v_mov_b32_e32 v68, v0
	v_mov_b32_e32 v69, v0
	v_mov_b32_e32 v70, v0
	v_mov_b32_e32 v71, v0
	v_mov_b32_e32 v72, v0
	v_mov_b32_e32 v73, v0
	v_mov_b32_e32 v74, v0
	v_mov_b32_e32 v75, v0
	v_mov_b32_e32 v76, v0
	v_mov_b32_e32 v77, v0
	v_mov_b32_e32 v78, v0
	v_mov_b32_e32 v79, v0
	v_mov_b32_e32 v80, v0
	v_mov_b32_e32 v81, v0
	v_mov_b32_e32 v82, v0
	v_mov_b32_e32 v83, v0
	v_mov_b32_e32 v84, v0
	v_mov_b32_e32 v85, v0
	v_mov_b32_e32 v86, v0
	v_mov_b32_e32 v87, v0
	v_mov_b32_e32 v88, v0
	v_mov_b32_e32 v89, v0
	v_mov_b32_e32 v90, v0
	v_mov_b32_e32 v91, v0
	v_mov_b32_e32 v92, v0
	v_mov_b32_e32 v93, v0
	v_mov_b32_e32 v94, v0
	v_mov_b32_e32 v95, v0
	v_mov_b32_e32 v96, v0
	v_mov_b32_e32 v97, v0
	v_mov_b32_e32 v98, v0
	v_mov_b32_e32 v99, v0
	v_mov_b32_e32 v100, v0
	v_mov_b32_e32 v101, v0
	v_mov_b32_e32 v102, v0
	v_mov_b32_e32 v103, v0
	v_mov_b32_e32 v104, v0
	v_mov_b32_e32 v105, v0
	v_mov_b32_e32 v106, v0
	v_mov_b32_e32 v107, v0
	v_mov_b32_e32 v108, v0
	v_mov_b32_e32 v109, v0
	v_mov_b32_e32 v110, v0
	v_mov_b32_e32 v111, v0
	v_mov_b32_e32 v112, v0
	v_mov_b32_e32 v113, v0
	v_mov_b32_e32 v114, v0
	v_mov_b32_e32 v115, v0
	v_mov_b32_e32 v116, v0
	v_mov_b32_e32 v117, v0
	v_mov_b32_e32 v118, v0
	v_mov_b32_e32 v119, v0
	v_mov_b32_e32 v120, v0
	v_mov_b32_e32 v121, v0
	v_mov_b32_e32 v122, v0
	v_mov_b32_e32 v123, v0
	v_mov_b32_e32 v124, v0
	v_mov_b32_e32 v125, v0
	v_mov_b32_e32 v126, v0
	v_mov_b32_e32 v127, v0
	.p2align	6

.LBB0_2045:
	s_and_b32 s22, s18, 3
	s_mov_b64 s[18:19], 0x80
	s_add_i32 m0, s58, 0x18000
	v_lshl_add_u64 v[2:3], v[2:3], 0, s[18:19]
	s_lshl_b32 s23, s9, 13
	s_lshl_b32 s24, s22, 12
	s_waitcnt vmcnt(4)
	s_barrier
	global_load_lds_dwordx4 v[2:3], off
	s_add_i32 m0, s58, 0x1a000
	s_add_u32 s20, s48, 0x8000
	v_lshl_add_u64 v[0:1], v[0:1], 0, s[18:19]
	s_addc_u32 s21, s49, 0
	s_add_i32 s62, s58, 0x8000
	global_load_lds_dwordx4 v[0:1], off
	v_lshl_add_u64 v[0:1], s[20:21], 0, v[134:135]
	s_mov_b32 m0, s62
	s_add_i32 s63, s58, 0xa000
	global_load_lds_dwordx4 v[0:1], off
	v_lshl_add_u64 v[0:1], s[20:21], 0, v[130:131]
	s_add_u32 s20, s40, 0x100080
	s_mov_b32 m0, s63
	s_addc_u32 s21, s41, 0
	global_load_lds_dwordx4 v[0:1], off
	s_add_i32 m0, s58, 0x1c000
	v_lshl_add_u64 v[0:1], s[20:21], 0, v[132:133]
	global_load_lds_dwordx4 v[0:1], off
	v_lshl_add_u64 v[0:1], s[20:21], 0, v[128:129]
	s_add_i32 m0, s58, 0x1e000
	s_ashr_i32 s64, s42, 31
	global_load_lds_dwordx4 v[0:1], off
	v_bfe_u32 v1, v4, 4, 2
	v_and_b32_e32 v0, 15, v4
	v_lshlrev_b32_e32 v2, 4, v1
	v_lshl_or_b32 v152, s9, 6, v0
	v_lshl_or_b32 v0, v0, 6, v2
	v_lshlrev_b32_e32 v2, 2, v4
	v_and_b32_e32 v2, 32, v2
	v_bitop3_b32 v3, v0, s23, v2 bitop3:0xde
	v_bitop3_b32 v153, v0, s24, v2 bitop3:0xde
	v_lshlrev_b32_e32 v0, 2, v1
	v_lshl_or_b32 v154, s22, 5, v0
	v_lshlrev_b32_e32 v0, 10, v5
	v_and_b32_e32 v0, 0xfffff800, v0
	v_lshl_add_u32 v0, v6, 7, v0
	v_and_b32_e32 v1, 1, v5
	v_lshl_or_b32 v0, v1, 6, v0
	v_lshl_add_u32 v136, v7, 1, v0
	v_lshlrev_b32_e32 v0, 10, v8
	v_and_b32_e32 v0, 0xfffff800, v0
	s_waitcnt vmcnt(6)
	s_add_u32 s66, s16, 0x780000
	v_lshl_add_u32 v0, v9, 7, v0
	v_and_b32_e32 v1, 1, v8
	s_addc_u32 s67, s17, 0
	v_lshl_or_b32 v0, v1, 6, v0
	s_add_i32 s68, 0, 0x10000
	s_add_i32 s69, 0, 0x14000
	s_sext_i32_i8 s75, s8
	s_mov_b32 s65, s42
	v_mov_b32_e32 v137, v133
	v_lshl_add_u32 v138, v10, 1, v0
	v_mov_b32_e32 v139, v133
	v_mov_b64_e32 v[140:141], 0xc0
	v_mov_b64_e32 v[142:143], 0xbf
	v_add_u32_e32 v155, s68, v153
	v_add_u32_e32 v156, 0, v3
	v_add_u32_e32 v157, s69, v153
	s_mov_b64 s[20:21], 0x80000
	s_mov_b32 s70, 0x80000
	s_mov_b64 s[22:23], 0x90000
	s_mov_b32 s71, 0x90000
	s_mov_b64 s[24:25], 0xa0000
	s_mov_b32 s72, 0xa0000
	s_mov_b64 s[26:27], 0xb0000
	s_mov_b32 s73, 0xb0000
	s_mov_b32 s74, 0
	s_barrier
	.p2align	6

.LBB0_2048:
	s_ashr_i32 s31, s30, 31
	v_cmp_lt_i64_e32 vcc, s[34:35], v[140:141]
	s_lshl_b64 s[34:35], s[30:31], 21
	s_add_u32 s34, s55, s34
	s_addc_u32 s35, s56, s35
	s_and_b64 s[36:37], vcc, exec
	s_cselect_b32 s31, s35, s49
	s_cselect_b32 s76, s34, s48
	s_ashr_i32 s29, s28, 31
	s_lshl_b64 s[36:37], s[28:29], 21
	s_add_u32 s36, s47, s36
	s_addc_u32 s37, s54, s37
	s_and_b64 s[50:51], vcc, exec
	s_cselect_b32 s29, s37, s41
	s_cselect_b32 s77, s36, s40
	s_add_u32 s78, s40, 0x100
	s_addc_u32 s79, s41, 0
	s_add_u32 s40, s48, 0xc000
	v_mov_b32_e32 v0, 0
	s_addc_u32 s41, s49, 0
	s_mov_b32 s80, -2
	v_mov_b32_e32 v1, v0
	v_mov_b32_e32 v2, v0
	v_mov_b32_e32 v3, v0
	v_mov_b32_e32 v4, v0
	v_mov_b32_e32 v5, v0
	v_mov_b32_e32 v6, v0
	v_mov_b32_e32 v7, v0
	v_mov_b32_e32 v16, v0
	v_mov_b32_e32 v17, v0
	v_mov_b32_e32 v18, v0
	v_mov_b32_e32 v19, v0
	v_mov_b32_e32 v20, v0
	v_mov_b32_e32 v21, v0
	v_mov_b32_e32 v22, v0
	v_mov_b32_e32 v23, v0
	v_mov_b32_e32 v32, v0
	v_mov_b32_e32 v33, v0
	v_mov_b32_e32 v34, v0
	v_mov_b32_e32 v35, v0
	v_mov_b32_e32 v36, v0
	v_mov_b32_e32 v37, v0
	v_mov_b32_e32 v38, v0
	v_mov_b32_e32 v39, v0
	v_mov_b32_e32 v48, v0
	v_mov_b32_e32 v49, v0
	v_mov_b32_e32 v50, v0
	v_mov_b32_e32 v51, v0
	v_mov_b32_e32 v52, v0
	v_mov_b32_e32 v53, v0
	v_mov_b32_e32 v54, v0
	v_mov_b32_e32 v55, v0
	v_mov_b32_e32 v8, v0
	v_mov_b32_e32 v9, v0
	v_mov_b32_e32 v10, v0
	v_mov_b32_e32 v11, v0
	v_mov_b32_e32 v12, v0
	v_mov_b32_e32 v13, v0
	v_mov_b32_e32 v14, v0
	v_mov_b32_e32 v15, v0
	v_mov_b32_e32 v24, v0
	v_mov_b32_e32 v25, v0
	v_mov_b32_e32 v26, v0
	v_mov_b32_e32 v27, v0
	v_mov_b32_e32 v28, v0
	v_mov_b32_e32 v29, v0
	v_mov_b32_e32 v30, v0
	v_mov_b32_e32 v31, v0
	v_mov_b32_e32 v40, v0
	v_mov_b32_e32 v41, v0
	v_mov_b32_e32 v42, v0
	v_mov_b32_e32 v43, v0
	v_mov_b32_e32 v44, v0
	v_mov_b32_e32 v45, v0
	v_mov_b32_e32 v46, v0
	v_mov_b32_e32 v47, v0
	v_mov_b32_e32 v56, v0
	v_mov_b32_e32 v57, v0
	v_mov_b32_e32 v58, v0
	v_mov_b32_e32 v59, v0
	v_mov_b32_e32 v60, v0
	v_mov_b32_e32 v61, v0
	v_mov_b32_e32 v62, v0
	v_mov_b32_e32 v63, v0
	v_mov_b32_e32 v64, v0
	v_mov_b32_e32 v65, v0
	v_mov_b32_e32 v66, v0
	v_mov_b32_e32 v67, v0
	v_mov_b32_e32 v68, v0
	v_mov_b32_e32 v69, v0
	v_mov_b32_e32 v70, v0
	v_mov_b32_e32 v71, v0
	v_mov_b32_e32 v80, v0
	v_mov_b32_e32 v81, v0
	v_mov_b32_e32 v82, v0
	v_mov_b32_e32 v83, v0
	v_mov_b32_e32 v84, v0
	v_mov_b32_e32 v85, v0
	v_mov_b32_e32 v86, v0
	v_mov_b32_e32 v87, v0
	v_mov_b32_e32 v96, v0
	v_mov_b32_e32 v97, v0
	v_mov_b32_e32 v98, v0
	v_mov_b32_e32 v99, v0
	v_mov_b32_e32 v100, v0
	v_mov_b32_e32 v101, v0
	v_mov_b32_e32 v102, v0
	v_mov_b32_e32 v103, v0
	v_mov_b32_e32 v112, v0
	v_mov_b32_e32 v113, v0
	v_mov_b32_e32 v114, v0
	v_mov_b32_e32 v115, v0
	v_mov_b32_e32 v116, v0
	v_mov_b32_e32 v117, v0
	v_mov_b32_e32 v118, v0
	v_mov_b32_e32 v119, v0
	v_mov_b32_e32 v72, v0
	v_mov_b32_e32 v73, v0
	v_mov_b32_e32 v74, v0
	v_mov_b32_e32 v75, v0
	v_mov_b32_e32 v76, v0
	v_mov_b32_e32 v77, v0
	v_mov_b32_e32 v78, v0
	v_mov_b32_e32 v79, v0
	v_mov_b32_e32 v88, v0
	v_mov_b32_e32 v89, v0
	v_mov_b32_e32 v90, v0
	v_mov_b32_e32 v91, v0
	v_mov_b32_e32 v92, v0
	v_mov_b32_e32 v93, v0
	v_mov_b32_e32 v94, v0
	v_mov_b32_e32 v95, v0
	v_mov_b32_e32 v104, v0
	v_mov_b32_e32 v105, v0
	v_mov_b32_e32 v106, v0
	v_mov_b32_e32 v107, v0
	v_mov_b32_e32 v108, v0
	v_mov_b32_e32 v109, v0
	v_mov_b32_e32 v110, v0
	v_mov_b32_e32 v111, v0
	v_mov_b32_e32 v120, v0
	v_mov_b32_e32 v121, v0
	v_mov_b32_e32 v122, v0
	v_mov_b32_e32 v123, v0
	v_mov_b32_e32 v124, v0
	v_mov_b32_e32 v125, v0
	v_mov_b32_e32 v126, v0
	v_mov_b32_e32 v127, v0
	.p2align	6
